# attention loop: separate loop copies for the two waves of each SIMD pair with alternating s_setprio per PV group (older 1,0,1,0 / younger 0,1,0,1)
# baseline (speedup 1.0000x reference)
; __device__ __forceinline__ int opaque_tid(int wv) { int lane_; asm volatile("v_mbcnt_lo_u32_b32 %0, -1, 0\n\tv_mbcnt_hi_u32_b32 %0, -1, %0" : "=v"(lane_)); return wv * 64 + lane_; }
; #define SBAR() __builtin_amdgcn_sched_barrier(0)
; __device__ __forceinline__ int v_rd_base(int lane) { return ((lane & 3) << 3) | (((lane >> 2) & 3) << 6) | (((lane >> 4) & 1) << 5) | (((lane >> 5) & 1) << 8); }
; __device__ __forceinline__ void diff_unit(const DiffArgs& A, int b, int h, int qb, char* lds, int wv) {
;     ...
;     float l_reg = 0; f32x16 o[4] = {}; bf16x8 qr[4];
;     { const char* Qw = Pb + (size_t)(qb * 128 + wq * 32) * (INC * 2) + (C_DQ + c * 64) * 2; const unsigned qoff = (unsigned)((r32 * INC + hi * 8) * 2);
; #pragma unroll
;       for (int d0 = 0; d0 < 4; ++d0) qr[d0] = *reinterpret_cast<const bf16x8*>(Qw + qoff + d0 * 32); }
;     const int colB0 = c * 128;
;     const int krow = wid * 4 + (lane >> 4), kcc = (lane & 15) ^ (krow & 15);
;     const unsigned koff = (unsigned)((krow * INC + kcc * 8) * 2);
;     const int vkey = (wid >> 2) * 16 + (((wid >> 1) & 1) << 3) + (((lane >> 4) & 1) << 2) + ((lane >> 2) & 3)  , vcol = ((wid & 1) * 2 + (lane >> 5)) * 32 + (lane & 3) * 8;
;     const unsigned voff = (unsigned)((vkey * INC + vcol) * 2 + (C_DV - C_DK) * 2);
;     const int vb0 = (int)(uintptr_t)V_lds + v_rd_base(lane);
;     const char* Pk = Pb + (size_t)(t_lo * KVBLK) * (INC * 2) + C_DK * 2; int iposk = ipos - t_lo * KVBLK - 4 * hi; asm volatile("" : "+v"(iposk));     const int relw = t_lo * KVBLK - (qb * 128 + wq * 32);
;     typedef __attribute__((address_space(3))) unsigned lds_u32;
;     __attribute__((address_space(3))) unsigned char* ldsA = (__attribute__((address_space(3))) unsigned char*)lds + wid * 1024;
;     ...
;     f32x16 pA0, pA1, pB0, pB1; bf16x8 pa0, pa1, pa2, pa3; const int NT = nt;
;     STAGE(0); ENDI();
;     STAGE(1);
;     BIAS(pA0, pA1, 0); qkt<4>(pA0, pA1, K_lds, qr, r32, hi, colB0);
;     ...
;     if (c == 0) {
;     ...
;         const int lp_ = opaque_tid(wv) & 63, r32p = lp_ & 31, hip = lp_ >> 5;
;         exp_half(pA0);
;         ENDI();
; #pragma unroll 1
;         for (int j = 1; j + 1 < NT; j += 2) {
;             STAGE(j + 1);
;             SBAR(); BIAS(pB0, pB1, j); qkt<4>(pB0, pB1, K_lds + SLOT(j), qr, r32p, hip, colB0);
;             exp_half(pA1); pack_p(pA0, pA1, l_reg, pa0, pa1, pa2, pa3); SBAR();
.Lsym_entry:
	v_mov_b32_e32 v0, 0
	v_mov_b32_e32 v1, 0
	v_mov_b32_e32 v2, 0
	v_mov_b32_e32 v3, 0
	v_mov_b32_e32 v4, 0
	v_mov_b32_e32 v5, 0
	v_mov_b32_e32 v6, 0
	v_mov_b32_e32 v7, 0
	v_mov_b32_e32 v8, 0
	v_mov_b32_e32 v9, 0
	v_mov_b32_e32 v10, 0
	v_mov_b32_e32 v11, 0
	v_mov_b32_e32 v12, 0
	v_mov_b32_e32 v13, 0
	v_mov_b32_e32 v14, 0
	v_mov_b32_e32 v15, 0
	v_mov_b32_e32 v16, 0
	v_mov_b32_e32 v17, 0
	v_mov_b32_e32 v18, 0
	v_mov_b32_e32 v19, 0
	v_mov_b32_e32 v20, 0
	v_mov_b32_e32 v21, 0
	v_mov_b32_e32 v22, 0
	v_mov_b32_e32 v23, 0
	v_mov_b32_e32 v24, 0
	v_mov_b32_e32 v25, 0
	v_mov_b32_e32 v26, 0
	v_mov_b32_e32 v27, 0
	v_mov_b32_e32 v28, 0
	v_mov_b32_e32 v29, 0
	v_mov_b32_e32 v30, 0
	v_mov_b32_e32 v31, 0
	v_mov_b32_e32 v32, 0
	v_mov_b32_e32 v33, 0
	v_mov_b32_e32 v34, 0
	v_mov_b32_e32 v35, 0
	v_mov_b32_e32 v36, 0
	v_mov_b32_e32 v37, 0
	v_mov_b32_e32 v38, 0
	v_mov_b32_e32 v39, 0
	v_mov_b32_e32 v40, 0
	v_mov_b32_e32 v41, 0
	v_mov_b32_e32 v42, 0
	v_mov_b32_e32 v43, 0
	v_mov_b32_e32 v44, 0
	v_mov_b32_e32 v45, 0
	v_mov_b32_e32 v46, 0
	v_mov_b32_e32 v47, 0
	v_mov_b32_e32 v48, 0
	v_mov_b32_e32 v49, 0
	v_mov_b32_e32 v50, 0
	v_mov_b32_e32 v51, 0
	v_mov_b32_e32 v52, 0
	v_mov_b32_e32 v53, 0
	v_mov_b32_e32 v54, 0
	v_mov_b32_e32 v55, 0
	v_mov_b32_e32 v56, 0
	v_mov_b32_e32 v57, 0
	v_mov_b32_e32 v58, 0
	v_mov_b32_e32 v59, 0
	v_mov_b32_e32 v60, 0
	v_mov_b32_e32 v61, 0
	v_mov_b32_e32 v62, 0
	v_mov_b32_e32 v63, 0
	v_mov_b32_e32 v182, 0
	v_mbcnt_lo_u32_b32 v190, -1, 0
	v_mbcnt_hi_u32_b32 v190, -1, v190
	v_and_b32_e32 v191, 31, v190
	v_lshrrev_b32_e32 v187, 5, v190
	v_lshlrev_b32_e32 v185, 4, v187
	v_or_b32_e32 v185, s52, v185
	v_and_b32_e32 v183, 15, v191
	v_lshlrev_b32_e32 v183, 4, v183
	v_xor_b32_e32 v185, v185, v183
	v_lshlrev_b32_e32 v183, 8, v191
	v_xor_b32_e32 v178, 0, v185
	v_add_u32_e32 v178, v178, v183
	v_add_u32_e32 v178, 0x10000, v178
	v_xor_b32_e32 v179, 32, v185
	v_add_u32_e32 v179, v179, v183
	v_add_u32_e32 v179, 0x10000, v179
	v_xor_b32_e32 v180, 64, v185
	v_add_u32_e32 v180, v180, v183
	v_add_u32_e32 v180, 0x10000, v180
	v_xor_b32_e32 v181, 96, v185
	v_add_u32_e32 v181, v181, v183
	v_add_u32_e32 v181, 0x10000, v181
	s_add_i32 s55, s63, 64
	v_subrev_u32_e32 v183, 64, v236
	v_cvt_f32_i32_e32 v183, v183
	s_mov_b32 s54, 0
	s_add_u32 s56, s20, 0x1c1e00
	s_addc_u32 s57, s21, 0
	v_exp_f32_e32 v80, v80
	v_exp_f32_e32 v81, v81
	v_exp_f32_e32 v82, v82
	v_exp_f32_e32 v83, v83
	v_add_f32_e32 v182, v80, v182
	v_add_f32_e32 v182, v81, v182
	v_cvt_pk_bf16_f32 v128, v80, v81
	v_exp_f32_e32 v84, v84
	v_exp_f32_e32 v85, v85
	v_add_f32_e32 v182, v82, v182
	v_add_f32_e32 v182, v83, v182
	v_cvt_pk_bf16_f32 v129, v82, v83
	v_exp_f32_e32 v86, v86
	v_exp_f32_e32 v87, v87
	v_add_f32_e32 v182, v84, v182
	v_add_f32_e32 v182, v85, v182
	v_cvt_pk_bf16_f32 v130, v84, v85
	v_cvt_pk_bf16_f32 v131, v86, v87
	v_add_f32_e32 v182, v86, v182
	v_add_f32_e32 v182, v87, v182
	s_cmp_lt_u32 s3, 0x100
	s_cbranch_scc0 .Lsym_loop_y

; #define SBAR() __builtin_amdgcn_sched_barrier(0)
; template <int KS> __device__ __forceinline__ void pv_ks(f32x16* o, int vb, bf16x8 pa) {
;     const s16x4 l0 = tr_read<v_rd_off(0, KS, 0)>(vb), h0 = tr_read<v_rd_off(0, KS, 1)>(vb), l1 = tr_read<v_rd_off(1, KS, 0)>(vb), h1 = tr_read<v_rd_off(1, KS, 1)>(vb);
;     const s16x4 l2 = tr_read<v_rd_off(2, KS, 0)>(vb), h2 = tr_read<v_rd_off(2, KS, 1)>(vb), l3 = tr_read<v_rd_off(3, KS, 0)>(vb), h3 = tr_read<v_rd_off(3, KS, 1)>(vb);
;     ...
;     asm volatile("s_waitcnt lgkmcnt(6)" ::: "memory"); SBAR();
;     o[0] = __builtin_amdgcn_mfma_f32_32x32x16_bf16(pa, PK(l0, h0), o[0], 0, 0, 0);
;     asm volatile("s_waitcnt lgkmcnt(4)" ::: "memory"); SBAR();
;     o[1] = __builtin_amdgcn_mfma_f32_32x32x16_bf16(pa, PK(l1, h1), o[1], 0, 0, 0);
;     asm volatile("s_waitcnt lgkmcnt(2)" ::: "memory"); SBAR();
;     o[2] = __builtin_amdgcn_mfma_f32_32x32x16_bf16(pa, PK(l2, h2), o[2], 0, 0, 0);
;     asm volatile("s_waitcnt lgkmcnt(0)" ::: "memory"); SBAR();
;     o[3] = __builtin_amdgcn_mfma_f32_32x32x16_bf16(pa, PK(l3, h3), o[3], 0, 0, 0);
;     ...
; }
; __device__ __forceinline__ void pv_d0(f32x16* o, int vb, bf16x8 pa0, bf16x8 pa1, bf16x8 pa2, bf16x8 pa3) {
;     __builtin_amdgcn_s_setprio(1);
;     pv_ks<0>(o, vb, pa0); pv_ks<1>(o, vb, pa1); pv_ks<2>(o, vb, pa2); pv_ks<3>(o, vb, pa3);
;     __builtin_amdgcn_s_setprio(0);
; }
; __device__ __forceinline__ void exp_half(f32x16& p) {
; #pragma unroll
;     for (int r = 0; r < 16; ++r) p[r] = __builtin_amdgcn_exp2f(p[r]);
; }
; __device__ __forceinline__ void pack_p(const f32x16& p0, const f32x16& p1, float& l_reg, bf16x8& pa0, bf16x8& pa1, bf16x8& pa2, bf16x8& pa3) {
;     float ps = 0;
; #pragma unroll
;     for (int r = 0; r < 16; ++r) ps += p0[r];
; #pragma unroll
;     for (int r = 0; r < 16; ++r) ps += p1[r];
;     l_reg += ps;
;     ...
;     PK4(p0, 0, pa0); PK4(p0, 8, pa1); PK4(p1, 0, pa2); PK4(p1, 8, pa3);
;     ...
; }
; __device__ __forceinline__ void diff_unit(const DiffArgs& A, int b, int h, int qb, char* lds, int wv) {
;     ...
;         for (int j = 1; j + 1 < NT; j += 2) {
;             STAGE(j + 1);
;             SBAR(); BIAS(pB0, pB1, j); qkt<4>(pB0, pB1, K_lds + SLOT(j), qr, r32p, hip, colB0);
;             exp_half(pA1); pack_p(pA0, pA1, l_reg, pa0, pa1, pa2, pa3); SBAR();
;             pv_d0(o, vb0 + SLOT(j - 1), pa0, pa1, pa2, pa3); exp_half(pB0);
;             ENDI();
;             STAGE(j + 2);
.Lsym_biasdone_xs0:
	s_add_i32 s55, s55, 64
	v_add_f32_e32 v183, 0xc2800000, v183
	ds_read_b64_tr_b16 v[144:145], v252 offset:0
	ds_read_b64_tr_b16 v[146:147], v252 offset:2048
	ds_read_b64_tr_b16 v[148:149], v252 offset:512
	ds_read_b64_tr_b16 v[150:151], v252 offset:2560
	ds_read_b64_tr_b16 v[152:153], v252 offset:1024
	ds_read_b64_tr_b16 v[154:155], v252 offset:3072
	ds_read_b64_tr_b16 v[156:157], v252 offset:1536
	ds_read_b64_tr_b16 v[158:159], v252 offset:3584
	s_setprio 1
	s_waitcnt lgkmcnt(4)
	v_mfma_f32_32x32x16_bf16 v[48:63], v[128:131], v[144:147], v[48:63]
	ds_read_b64_tr_b16 v[144:145], v252 offset:4096
	ds_read_b64_tr_b16 v[146:147], v252 offset:6144
	v_exp_f32_e32 v88, v88
	v_exp_f32_e32 v89, v89
	v_mfma_f32_32x32x16_bf16 v[32:47], v[128:131], v[148:151], v[32:47]
	ds_read_b64_tr_b16 v[148:149], v252 offset:4608
	ds_read_b64_tr_b16 v[150:151], v252 offset:6656
	v_exp_f32_e32 v90, v90
	v_exp_f32_e32 v91, v91
	v_add_f32_e32 v182, v88, v182
	v_add_f32_e32 v182, v89, v182
	v_cvt_pk_bf16_f32 v132, v88, v89
	s_waitcnt lgkmcnt(4)
	v_mfma_f32_32x32x16_bf16 v[16:31], v[128:131], v[152:155], v[16:31]
	ds_read_b64_tr_b16 v[152:153], v252 offset:5120
	ds_read_b64_tr_b16 v[154:155], v252 offset:7168
	v_exp_f32_e32 v92, v92
	v_exp_f32_e32 v93, v93
	v_add_f32_e32 v182, v90, v182
	v_add_f32_e32 v182, v91, v182
	v_cvt_pk_bf16_f32 v133, v90, v91
	v_mfma_f32_32x32x16_bf16 v[0:15], v[128:131], v[156:159], v[0:15]
	ds_read_b64_tr_b16 v[156:157], v252 offset:5632
	ds_read_b64_tr_b16 v[158:159], v252 offset:7680
	v_exp_f32_e32 v94, v94
	v_exp_f32_e32 v95, v95
	v_add_f32_e32 v182, v92, v182
	v_add_f32_e32 v182, v93, v182
	v_cvt_pk_bf16_f32 v134, v92, v93
	v_cvt_pk_bf16_f32 v135, v94, v95
	v_add_f32_e32 v182, v94, v182
	v_add_f32_e32 v182, v95, v182
	v_mfma_f32_32x32x16_bf16 v[112:127], v[192:195], v[172:175], v[112:127]
	v_mfma_f32_32x32x16_bf16 v[96:111], v[196:199], v[172:175], v[96:111]
	v_mfma_f32_32x32x16_bf16 v[112:127], v[200:203], v[168:171], v[112:127]
	v_mfma_f32_32x32x16_bf16 v[96:111], v[204:207], v[168:171], v[96:111]
	s_setprio 0
	s_waitcnt lgkmcnt(4)
	v_mfma_f32_32x32x16_bf16 v[48:63], v[132:135], v[144:147], v[48:63]
	ds_read_b64_tr_b16 v[144:145], v252 offset:8192
	ds_read_b64_tr_b16 v[146:147], v252 offset:10240
	v_exp_f32_e32 v64, v64
	v_exp_f32_e32 v65, v65
	v_mfma_f32_32x32x16_bf16 v[32:47], v[132:135], v[148:151], v[32:47]
	ds_read_b64_tr_b16 v[148:149], v252 offset:8704
	ds_read_b64_tr_b16 v[150:151], v252 offset:10752
	v_exp_f32_e32 v66, v66
	v_exp_f32_e32 v67, v67
	v_add_f32_e32 v182, v64, v182
	v_add_f32_e32 v182, v65, v182
	v_cvt_pk_bf16_f32 v136, v64, v65
	s_waitcnt lgkmcnt(4)
	v_mfma_f32_32x32x16_bf16 v[16:31], v[132:135], v[152:155], v[16:31]
	ds_read_b64_tr_b16 v[152:153], v252 offset:9216
	ds_read_b64_tr_b16 v[154:155], v252 offset:11264
	v_exp_f32_e32 v68, v68
	v_exp_f32_e32 v69, v69
	v_add_f32_e32 v182, v66, v182
	v_add_f32_e32 v182, v67, v182
	v_cvt_pk_bf16_f32 v137, v66, v67
	v_mfma_f32_32x32x16_bf16 v[0:15], v[132:135], v[156:159], v[0:15]
	ds_read_b64_tr_b16 v[156:157], v252 offset:9728
	ds_read_b64_tr_b16 v[158:159], v252 offset:11776
	v_exp_f32_e32 v70, v70
	v_exp_f32_e32 v71, v71
	v_add_f32_e32 v182, v68, v182
	v_add_f32_e32 v182, v69, v182
	v_cvt_pk_bf16_f32 v138, v68, v69
	v_cvt_pk_bf16_f32 v139, v70, v71
	v_add_f32_e32 v182, v70, v182
	v_add_f32_e32 v182, v71, v182
	v_mfma_f32_32x32x16_bf16 v[112:127], v[208:211], v[164:167], v[112:127]
	v_mfma_f32_32x32x16_bf16 v[96:111], v[212:215], v[164:167], v[96:111]
	v_mfma_f32_32x32x16_bf16 v[112:127], v[216:219], v[160:163], v[112:127]
	v_mfma_f32_32x32x16_bf16 v[96:111], v[220:223], v[160:163], v[96:111]
	s_setprio 1
	s_waitcnt lgkmcnt(4)
	v_mfma_f32_32x32x16_bf16 v[48:63], v[136:139], v[144:147], v[48:63]
	ds_read_b64_tr_b16 v[144:145], v252 offset:12288
	ds_read_b64_tr_b16 v[146:147], v252 offset:14336
	v_exp_f32_e32 v72, v72
	v_exp_f32_e32 v73, v73
	v_mfma_f32_32x32x16_bf16 v[32:47], v[136:139], v[148:151], v[32:47]
	ds_read_b64_tr_b16 v[148:149], v252 offset:12800
	ds_read_b64_tr_b16 v[150:151], v252 offset:14848
	v_exp_f32_e32 v74, v74
	v_exp_f32_e32 v75, v75
	v_add_f32_e32 v182, v72, v182
	v_add_f32_e32 v182, v73, v182
	v_cvt_pk_bf16_f32 v140, v72, v73
	s_waitcnt lgkmcnt(4)
	v_mfma_f32_32x32x16_bf16 v[16:31], v[136:139], v[152:155], v[16:31]
	ds_read_b64_tr_b16 v[152:153], v252 offset:13312
	ds_read_b64_tr_b16 v[154:155], v252 offset:15360
	v_exp_f32_e32 v76, v76
	v_exp_f32_e32 v77, v77
	v_add_f32_e32 v182, v74, v182
	v_add_f32_e32 v182, v75, v182
	v_cvt_pk_bf16_f32 v141, v74, v75
	v_mfma_f32_32x32x16_bf16 v[0:15], v[136:139], v[156:159], v[0:15]
	ds_read_b64_tr_b16 v[156:157], v252 offset:13824
	ds_read_b64_tr_b16 v[158:159], v252 offset:15872
	v_exp_f32_e32 v78, v78
	v_exp_f32_e32 v79, v79
	v_add_f32_e32 v182, v76, v182
	v_add_f32_e32 v182, v77, v182
	v_cvt_pk_bf16_f32 v142, v76, v77
	v_cvt_pk_bf16_f32 v143, v78, v79
	v_add_f32_e32 v182, v78, v182
	v_add_f32_e32 v182, v79, v182
	s_setprio 0
	s_waitcnt lgkmcnt(4)
	v_mfma_f32_32x32x16_bf16 v[48:63], v[140:143], v[144:147], v[48:63]
	v_exp_f32_e32 v112, v112
	v_exp_f32_e32 v113, v113
	v_mfma_f32_32x32x16_bf16 v[32:47], v[140:143], v[148:151], v[32:47]
	v_exp_f32_e32 v114, v114
	v_exp_f32_e32 v115, v115
	v_add_f32_e32 v182, v112, v182
	v_add_f32_e32 v182, v113, v182
	v_cvt_pk_bf16_f32 v128, v112, v113
	s_waitcnt lgkmcnt(0)
	v_mfma_f32_32x32x16_bf16 v[16:31], v[140:143], v[152:155], v[16:31]
	v_exp_f32_e32 v116, v116
	v_exp_f32_e32 v117, v117
	v_add_f32_e32 v182, v114, v182
	v_add_f32_e32 v182, v115, v182
	v_cvt_pk_bf16_f32 v129, v114, v115
	v_mfma_f32_32x32x16_bf16 v[0:15], v[140:143], v[156:159], v[0:15]
	v_exp_f32_e32 v118, v118
	v_exp_f32_e32 v119, v119
	v_add_f32_e32 v182, v116, v182
	v_add_f32_e32 v182, v117, v182
	v_cvt_pk_bf16_f32 v130, v116, v117
	v_cvt_pk_bf16_f32 v131, v118, v119
	v_add_f32_e32 v182, v118, v182
	v_add_f32_e32 v182, v119, v182
	s_add_i32 s54, s54, 1
	s_cmp_ge_i32 s54, s62
	s_cbranch_scc1 .Lsym_last1_x
	s_waitcnt vmcnt(0)
	s_barrier
	ds_read_b128 v[192:195], v178 offset:32768
	ds_read_b128 v[196:199], v178 offset:40960
	ds_read_b128 v[200:203], v179 offset:32768
	ds_read_b128 v[204:207], v179 offset:40960
	ds_read_b128 v[208:211], v180 offset:32768
	ds_read_b128 v[212:215], v180 offset:40960
	ds_read_b128 v[216:219], v181 offset:32768
	ds_read_b128 v[220:223], v181 offset:40960
	s_add_i32 s53, s54, 2
	s_cmp_le_i32 s53, s62
	s_cbranch_scc0 .Lsym_nostage_xs1
	s_add_i32 m0, s25, 0xc000
	s_add_u32 s60, s56, 0x70000
	s_addc_u32 s61, s57, 0
	global_load_lds_dwordx4 v176, s[56:57]
	s_add_i32 m0, s24, 0xc000
	s_nop 0
	global_load_lds_dwordx4 v188, s[56:57]
	s_add_i32 m0, s25, 0xe000
	s_add_u32 s56, s56, 0xe0000
	s_addc_u32 s57, s57, 0
	global_load_lds_dwordx4 v176, s[60:61]
	s_add_i32 m0, s24, 0xe000
	s_nop 0
	global_load_lds_dwordx4 v188, s[60:61]

; #define SBAR() __builtin_amdgcn_sched_barrier(0)
; template <int KS> __device__ __forceinline__ void pv_ks(f32x16* o, int vb, bf16x8 pa) {
;     const s16x4 l0 = tr_read<v_rd_off(0, KS, 0)>(vb), h0 = tr_read<v_rd_off(0, KS, 1)>(vb), l1 = tr_read<v_rd_off(1, KS, 0)>(vb), h1 = tr_read<v_rd_off(1, KS, 1)>(vb);
;     const s16x4 l2 = tr_read<v_rd_off(2, KS, 0)>(vb), h2 = tr_read<v_rd_off(2, KS, 1)>(vb), l3 = tr_read<v_rd_off(3, KS, 0)>(vb), h3 = tr_read<v_rd_off(3, KS, 1)>(vb);
;     ...
;     asm volatile("s_waitcnt lgkmcnt(6)" ::: "memory"); SBAR();
;     o[0] = __builtin_amdgcn_mfma_f32_32x32x16_bf16(pa, PK(l0, h0), o[0], 0, 0, 0);
;     asm volatile("s_waitcnt lgkmcnt(4)" ::: "memory"); SBAR();
;     o[1] = __builtin_amdgcn_mfma_f32_32x32x16_bf16(pa, PK(l1, h1), o[1], 0, 0, 0);
;     asm volatile("s_waitcnt lgkmcnt(2)" ::: "memory"); SBAR();
;     o[2] = __builtin_amdgcn_mfma_f32_32x32x16_bf16(pa, PK(l2, h2), o[2], 0, 0, 0);
;     asm volatile("s_waitcnt lgkmcnt(0)" ::: "memory"); SBAR();
;     o[3] = __builtin_amdgcn_mfma_f32_32x32x16_bf16(pa, PK(l3, h3), o[3], 0, 0, 0);
;     ...
; }
; __device__ __forceinline__ void pv_d0(f32x16* o, int vb, bf16x8 pa0, bf16x8 pa1, bf16x8 pa2, bf16x8 pa3) {
;     __builtin_amdgcn_s_setprio(1);
;     pv_ks<0>(o, vb, pa0); pv_ks<1>(o, vb, pa1); pv_ks<2>(o, vb, pa2); pv_ks<3>(o, vb, pa3);
;     __builtin_amdgcn_s_setprio(0);
; }
; __device__ __forceinline__ void exp_half(f32x16& p) {
; #pragma unroll
;     for (int r = 0; r < 16; ++r) p[r] = __builtin_amdgcn_exp2f(p[r]);
; }
; __device__ __forceinline__ void pack_p(const f32x16& p0, const f32x16& p1, float& l_reg, bf16x8& pa0, bf16x8& pa1, bf16x8& pa2, bf16x8& pa3) {
;     float ps = 0;
; #pragma unroll
;     for (int r = 0; r < 16; ++r) ps += p0[r];
; #pragma unroll
;     for (int r = 0; r < 16; ++r) ps += p1[r];
;     l_reg += ps;
;     ...
;     PK4(p0, 0, pa0); PK4(p0, 8, pa1); PK4(p1, 0, pa2); PK4(p1, 8, pa3);
;     ...
; }
; __device__ __forceinline__ void diff_unit(const DiffArgs& A, int b, int h, int qb, char* lds, int wv) {
;     ...
;         for (int j = 1; j + 1 < NT; j += 2) {
;             STAGE(j + 1);
;             SBAR(); BIAS(pB0, pB1, j); qkt<4>(pB0, pB1, K_lds + SLOT(j), qr, r32p, hip, colB0);
;             exp_half(pA1); pack_p(pA0, pA1, l_reg, pa0, pa1, pa2, pa3); SBAR();
;             pv_d0(o, vb0 + SLOT(j - 1), pa0, pa1, pa2, pa3); exp_half(pB0);
;             ENDI();
;             STAGE(j + 2);
.Lsym_biasdone_xs1:
	s_add_i32 s55, s55, 64
	v_add_f32_e32 v183, 0xc2800000, v183
	ds_read_b64_tr_b16 v[144:145], v252 offset:16384
	ds_read_b64_tr_b16 v[146:147], v252 offset:18432
	ds_read_b64_tr_b16 v[148:149], v252 offset:16896
	ds_read_b64_tr_b16 v[150:151], v252 offset:18944
	ds_read_b64_tr_b16 v[152:153], v252 offset:17408
	ds_read_b64_tr_b16 v[154:155], v252 offset:19456
	ds_read_b64_tr_b16 v[156:157], v252 offset:17920
	ds_read_b64_tr_b16 v[158:159], v252 offset:19968
	s_setprio 1
	s_waitcnt lgkmcnt(4)
	v_mfma_f32_32x32x16_bf16 v[48:63], v[128:131], v[144:147], v[48:63]
	ds_read_b64_tr_b16 v[144:145], v252 offset:20480
	ds_read_b64_tr_b16 v[146:147], v252 offset:22528
	v_exp_f32_e32 v120, v120
	v_exp_f32_e32 v121, v121
	v_mfma_f32_32x32x16_bf16 v[32:47], v[128:131], v[148:151], v[32:47]
	ds_read_b64_tr_b16 v[148:149], v252 offset:20992
	ds_read_b64_tr_b16 v[150:151], v252 offset:23040
	v_exp_f32_e32 v122, v122
	v_exp_f32_e32 v123, v123
	v_add_f32_e32 v182, v120, v182
	v_add_f32_e32 v182, v121, v182
	v_cvt_pk_bf16_f32 v132, v120, v121
	s_waitcnt lgkmcnt(4)
	v_mfma_f32_32x32x16_bf16 v[16:31], v[128:131], v[152:155], v[16:31]
	ds_read_b64_tr_b16 v[152:153], v252 offset:21504
	ds_read_b64_tr_b16 v[154:155], v252 offset:23552
	v_exp_f32_e32 v124, v124
	v_exp_f32_e32 v125, v125
	v_add_f32_e32 v182, v122, v182
	v_add_f32_e32 v182, v123, v182
	v_cvt_pk_bf16_f32 v133, v122, v123
	v_mfma_f32_32x32x16_bf16 v[0:15], v[128:131], v[156:159], v[0:15]
	ds_read_b64_tr_b16 v[156:157], v252 offset:22016
	ds_read_b64_tr_b16 v[158:159], v252 offset:24064
	v_exp_f32_e32 v126, v126
	v_exp_f32_e32 v127, v127
	v_add_f32_e32 v182, v124, v182
	v_add_f32_e32 v182, v125, v182
	v_cvt_pk_bf16_f32 v134, v124, v125
	v_cvt_pk_bf16_f32 v135, v126, v127
	v_add_f32_e32 v182, v126, v182
	v_add_f32_e32 v182, v127, v182
	v_mfma_f32_32x32x16_bf16 v[80:95], v[192:195], v[172:175], v[80:95]
	v_mfma_f32_32x32x16_bf16 v[64:79], v[196:199], v[172:175], v[64:79]
	v_mfma_f32_32x32x16_bf16 v[80:95], v[200:203], v[168:171], v[80:95]
	v_mfma_f32_32x32x16_bf16 v[64:79], v[204:207], v[168:171], v[64:79]
	s_setprio 0
	s_waitcnt lgkmcnt(4)
	v_mfma_f32_32x32x16_bf16 v[48:63], v[132:135], v[144:147], v[48:63]
	ds_read_b64_tr_b16 v[144:145], v252 offset:24576
	ds_read_b64_tr_b16 v[146:147], v252 offset:26624
	v_exp_f32_e32 v96, v96
	v_exp_f32_e32 v97, v97
	v_mfma_f32_32x32x16_bf16 v[32:47], v[132:135], v[148:151], v[32:47]
	ds_read_b64_tr_b16 v[148:149], v252 offset:25088
	ds_read_b64_tr_b16 v[150:151], v252 offset:27136
	v_exp_f32_e32 v98, v98
	v_exp_f32_e32 v99, v99
	v_add_f32_e32 v182, v96, v182
	v_add_f32_e32 v182, v97, v182
	v_cvt_pk_bf16_f32 v136, v96, v97
	s_waitcnt lgkmcnt(4)
	v_mfma_f32_32x32x16_bf16 v[16:31], v[132:135], v[152:155], v[16:31]
	ds_read_b64_tr_b16 v[152:153], v252 offset:25600
	ds_read_b64_tr_b16 v[154:155], v252 offset:27648
	v_exp_f32_e32 v100, v100
	v_exp_f32_e32 v101, v101
	v_add_f32_e32 v182, v98, v182
	v_add_f32_e32 v182, v99, v182
	v_cvt_pk_bf16_f32 v137, v98, v99
	v_mfma_f32_32x32x16_bf16 v[0:15], v[132:135], v[156:159], v[0:15]
	ds_read_b64_tr_b16 v[156:157], v252 offset:26112
	ds_read_b64_tr_b16 v[158:159], v252 offset:28160
	v_exp_f32_e32 v102, v102
	v_exp_f32_e32 v103, v103
	v_add_f32_e32 v182, v100, v182
	v_add_f32_e32 v182, v101, v182
	v_cvt_pk_bf16_f32 v138, v100, v101
	v_cvt_pk_bf16_f32 v139, v102, v103
	v_add_f32_e32 v182, v102, v182
	v_add_f32_e32 v182, v103, v182
	v_mfma_f32_32x32x16_bf16 v[80:95], v[208:211], v[164:167], v[80:95]
	v_mfma_f32_32x32x16_bf16 v[64:79], v[212:215], v[164:167], v[64:79]
	v_mfma_f32_32x32x16_bf16 v[80:95], v[216:219], v[160:163], v[80:95]
	v_mfma_f32_32x32x16_bf16 v[64:79], v[220:223], v[160:163], v[64:79]
	s_setprio 1
	s_waitcnt lgkmcnt(4)
	v_mfma_f32_32x32x16_bf16 v[48:63], v[136:139], v[144:147], v[48:63]
	ds_read_b64_tr_b16 v[144:145], v252 offset:28672
	ds_read_b64_tr_b16 v[146:147], v252 offset:30720
	v_exp_f32_e32 v104, v104
	v_exp_f32_e32 v105, v105
	v_mfma_f32_32x32x16_bf16 v[32:47], v[136:139], v[148:151], v[32:47]
	ds_read_b64_tr_b16 v[148:149], v252 offset:29184
	ds_read_b64_tr_b16 v[150:151], v252 offset:31232
	v_exp_f32_e32 v106, v106
	v_exp_f32_e32 v107, v107
	v_add_f32_e32 v182, v104, v182
	v_add_f32_e32 v182, v105, v182
	v_cvt_pk_bf16_f32 v140, v104, v105
	s_waitcnt lgkmcnt(4)
	v_mfma_f32_32x32x16_bf16 v[16:31], v[136:139], v[152:155], v[16:31]
	ds_read_b64_tr_b16 v[152:153], v252 offset:29696
	ds_read_b64_tr_b16 v[154:155], v252 offset:31744
	v_exp_f32_e32 v108, v108
	v_exp_f32_e32 v109, v109
	v_add_f32_e32 v182, v106, v182
	v_add_f32_e32 v182, v107, v182
	v_cvt_pk_bf16_f32 v141, v106, v107
	v_mfma_f32_32x32x16_bf16 v[0:15], v[136:139], v[156:159], v[0:15]
	ds_read_b64_tr_b16 v[156:157], v252 offset:30208
	ds_read_b64_tr_b16 v[158:159], v252 offset:32256
	v_exp_f32_e32 v110, v110
	v_exp_f32_e32 v111, v111
	v_add_f32_e32 v182, v108, v182
	v_add_f32_e32 v182, v109, v182
	v_cvt_pk_bf16_f32 v142, v108, v109
	v_cvt_pk_bf16_f32 v143, v110, v111
	v_add_f32_e32 v182, v110, v182
	v_add_f32_e32 v182, v111, v182
	s_setprio 0
	s_waitcnt lgkmcnt(4)
	v_mfma_f32_32x32x16_bf16 v[48:63], v[140:143], v[144:147], v[48:63]
	v_exp_f32_e32 v80, v80
	v_exp_f32_e32 v81, v81
	v_mfma_f32_32x32x16_bf16 v[32:47], v[140:143], v[148:151], v[32:47]
	v_exp_f32_e32 v82, v82
	v_exp_f32_e32 v83, v83
	v_add_f32_e32 v182, v80, v182
	v_add_f32_e32 v182, v81, v182
	v_cvt_pk_bf16_f32 v128, v80, v81
	s_waitcnt lgkmcnt(0)
	v_mfma_f32_32x32x16_bf16 v[16:31], v[140:143], v[152:155], v[16:31]
	v_exp_f32_e32 v84, v84
	v_exp_f32_e32 v85, v85
	v_add_f32_e32 v182, v82, v182
	v_add_f32_e32 v182, v83, v182
	v_cvt_pk_bf16_f32 v129, v82, v83
	v_mfma_f32_32x32x16_bf16 v[0:15], v[140:143], v[156:159], v[0:15]
	v_exp_f32_e32 v86, v86
	v_exp_f32_e32 v87, v87
	v_add_f32_e32 v182, v84, v182
	v_add_f32_e32 v182, v85, v182
	v_cvt_pk_bf16_f32 v130, v84, v85
	v_cvt_pk_bf16_f32 v131, v86, v87
	v_add_f32_e32 v182, v86, v182
	v_add_f32_e32 v182, v87, v182
	s_add_i32 s54, s54, 1
	s_waitcnt vmcnt(0)
	s_barrier
	ds_read_b128 v[192:195], v178 offset:49152
	ds_read_b128 v[196:199], v178 offset:57344
	ds_read_b128 v[200:203], v179 offset:49152
	ds_read_b128 v[204:207], v179 offset:57344
	ds_read_b128 v[208:211], v180 offset:49152
	ds_read_b128 v[212:215], v180 offset:57344
	ds_read_b128 v[216:219], v181 offset:49152
	ds_read_b128 v[220:223], v181 offset:57344
	s_add_i32 s53, s54, 2
	s_cmp_le_i32 s53, s62
	s_cbranch_scc0 .Lsym_nostage_xs2
	s_add_i32 m0, s25, 0x0
	s_add_u32 s60, s56, 0x70000
	s_addc_u32 s61, s57, 0
	global_load_lds_dwordx4 v176, s[56:57]
	s_add_i32 m0, s24, 0x0
	s_nop 0
	global_load_lds_dwordx4 v188, s[56:57]
	s_add_i32 m0, s25, 0x2000
	s_add_u32 s56, s56, 0xe0000
	s_addc_u32 s57, s57, 0
	global_load_lds_dwordx4 v176, s[60:61]
	s_add_i32 m0, s24, 0x2000
	s_nop 0
	global_load_lds_dwordx4 v188, s[60:61]

; #define SBAR() __builtin_amdgcn_sched_barrier(0)
; template <int KS> __device__ __forceinline__ void pv_ks(f32x16* o, int vb, bf16x8 pa) {
;     const s16x4 l0 = tr_read<v_rd_off(0, KS, 0)>(vb), h0 = tr_read<v_rd_off(0, KS, 1)>(vb), l1 = tr_read<v_rd_off(1, KS, 0)>(vb), h1 = tr_read<v_rd_off(1, KS, 1)>(vb);
;     const s16x4 l2 = tr_read<v_rd_off(2, KS, 0)>(vb), h2 = tr_read<v_rd_off(2, KS, 1)>(vb), l3 = tr_read<v_rd_off(3, KS, 0)>(vb), h3 = tr_read<v_rd_off(3, KS, 1)>(vb);
;     ...
;     asm volatile("s_waitcnt lgkmcnt(6)" ::: "memory"); SBAR();
;     o[0] = __builtin_amdgcn_mfma_f32_32x32x16_bf16(pa, PK(l0, h0), o[0], 0, 0, 0);
;     asm volatile("s_waitcnt lgkmcnt(4)" ::: "memory"); SBAR();
;     o[1] = __builtin_amdgcn_mfma_f32_32x32x16_bf16(pa, PK(l1, h1), o[1], 0, 0, 0);
;     asm volatile("s_waitcnt lgkmcnt(2)" ::: "memory"); SBAR();
;     o[2] = __builtin_amdgcn_mfma_f32_32x32x16_bf16(pa, PK(l2, h2), o[2], 0, 0, 0);
;     asm volatile("s_waitcnt lgkmcnt(0)" ::: "memory"); SBAR();
;     o[3] = __builtin_amdgcn_mfma_f32_32x32x16_bf16(pa, PK(l3, h3), o[3], 0, 0, 0);
;     ...
; }
; __device__ __forceinline__ void pv_d0(f32x16* o, int vb, bf16x8 pa0, bf16x8 pa1, bf16x8 pa2, bf16x8 pa3) {
;     __builtin_amdgcn_s_setprio(1);
;     pv_ks<0>(o, vb, pa0); pv_ks<1>(o, vb, pa1); pv_ks<2>(o, vb, pa2); pv_ks<3>(o, vb, pa3);
;     __builtin_amdgcn_s_setprio(0);
; }
; __device__ __forceinline__ void exp_half(f32x16& p) {
; #pragma unroll
;     for (int r = 0; r < 16; ++r) p[r] = __builtin_amdgcn_exp2f(p[r]);
; }
; __device__ __forceinline__ void pack_p(const f32x16& p0, const f32x16& p1, float& l_reg, bf16x8& pa0, bf16x8& pa1, bf16x8& pa2, bf16x8& pa3) {
;     float ps = 0;
; #pragma unroll
;     for (int r = 0; r < 16; ++r) ps += p0[r];
; #pragma unroll
;     for (int r = 0; r < 16; ++r) ps += p1[r];
;     l_reg += ps;
;     ...
;     PK4(p0, 0, pa0); PK4(p0, 8, pa1); PK4(p1, 0, pa2); PK4(p1, 8, pa3);
;     ...
; }
; __device__ __forceinline__ void diff_unit(const DiffArgs& A, int b, int h, int qb, char* lds, int wv) {
;     ...
;         for (int j = 1; j + 1 < NT; j += 2) {
;             STAGE(j + 1);
;             SBAR(); BIAS(pB0, pB1, j); qkt<4>(pB0, pB1, K_lds + SLOT(j), qr, r32p, hip, colB0);
;             exp_half(pA1); pack_p(pA0, pA1, l_reg, pa0, pa1, pa2, pa3); SBAR();
;             pv_d0(o, vb0 + SLOT(j - 1), pa0, pa1, pa2, pa3); exp_half(pB0);
;             ENDI();
;             STAGE(j + 2);
.Lsym_biasdone_xs2:
	s_add_i32 s55, s55, 64
	v_add_f32_e32 v183, 0xc2800000, v183
	ds_read_b64_tr_b16 v[144:145], v252 offset:32768
	ds_read_b64_tr_b16 v[146:147], v252 offset:34816
	ds_read_b64_tr_b16 v[148:149], v252 offset:33280
	ds_read_b64_tr_b16 v[150:151], v252 offset:35328
	ds_read_b64_tr_b16 v[152:153], v252 offset:33792
	ds_read_b64_tr_b16 v[154:155], v252 offset:35840
	ds_read_b64_tr_b16 v[156:157], v252 offset:34304
	ds_read_b64_tr_b16 v[158:159], v252 offset:36352
	s_setprio 1
	s_waitcnt lgkmcnt(4)
	v_mfma_f32_32x32x16_bf16 v[48:63], v[128:131], v[144:147], v[48:63]
	ds_read_b64_tr_b16 v[144:145], v252 offset:36864
	ds_read_b64_tr_b16 v[146:147], v252 offset:38912
	v_exp_f32_e32 v88, v88
	v_exp_f32_e32 v89, v89
	v_mfma_f32_32x32x16_bf16 v[32:47], v[128:131], v[148:151], v[32:47]
	ds_read_b64_tr_b16 v[148:149], v252 offset:37376
	ds_read_b64_tr_b16 v[150:151], v252 offset:39424
	v_exp_f32_e32 v90, v90
	v_exp_f32_e32 v91, v91
	v_add_f32_e32 v182, v88, v182
	v_add_f32_e32 v182, v89, v182
	v_cvt_pk_bf16_f32 v132, v88, v89
	s_waitcnt lgkmcnt(4)
	v_mfma_f32_32x32x16_bf16 v[16:31], v[128:131], v[152:155], v[16:31]
	ds_read_b64_tr_b16 v[152:153], v252 offset:37888
	ds_read_b64_tr_b16 v[154:155], v252 offset:39936
	v_exp_f32_e32 v92, v92
	v_exp_f32_e32 v93, v93
	v_add_f32_e32 v182, v90, v182
	v_add_f32_e32 v182, v91, v182
	v_cvt_pk_bf16_f32 v133, v90, v91
	v_mfma_f32_32x32x16_bf16 v[0:15], v[128:131], v[156:159], v[0:15]
	ds_read_b64_tr_b16 v[156:157], v252 offset:38400
	ds_read_b64_tr_b16 v[158:159], v252 offset:40448
	v_exp_f32_e32 v94, v94
	v_exp_f32_e32 v95, v95
	v_add_f32_e32 v182, v92, v182
	v_add_f32_e32 v182, v93, v182
	v_cvt_pk_bf16_f32 v134, v92, v93
	v_cvt_pk_bf16_f32 v135, v94, v95
	v_add_f32_e32 v182, v94, v182
	v_add_f32_e32 v182, v95, v182
	v_mfma_f32_32x32x16_bf16 v[112:127], v[192:195], v[172:175], v[112:127]
	v_mfma_f32_32x32x16_bf16 v[96:111], v[196:199], v[172:175], v[96:111]
	v_mfma_f32_32x32x16_bf16 v[112:127], v[200:203], v[168:171], v[112:127]
	v_mfma_f32_32x32x16_bf16 v[96:111], v[204:207], v[168:171], v[96:111]
	s_setprio 0
	s_waitcnt lgkmcnt(4)
	v_mfma_f32_32x32x16_bf16 v[48:63], v[132:135], v[144:147], v[48:63]
	ds_read_b64_tr_b16 v[144:145], v252 offset:40960
	ds_read_b64_tr_b16 v[146:147], v252 offset:43008
	v_exp_f32_e32 v64, v64
	v_exp_f32_e32 v65, v65
	v_mfma_f32_32x32x16_bf16 v[32:47], v[132:135], v[148:151], v[32:47]
	ds_read_b64_tr_b16 v[148:149], v252 offset:41472
	ds_read_b64_tr_b16 v[150:151], v252 offset:43520
	v_exp_f32_e32 v66, v66
	v_exp_f32_e32 v67, v67
	v_add_f32_e32 v182, v64, v182
	v_add_f32_e32 v182, v65, v182
	v_cvt_pk_bf16_f32 v136, v64, v65
	s_waitcnt lgkmcnt(4)
	v_mfma_f32_32x32x16_bf16 v[16:31], v[132:135], v[152:155], v[16:31]
	ds_read_b64_tr_b16 v[152:153], v252 offset:41984
	ds_read_b64_tr_b16 v[154:155], v252 offset:44032
	v_exp_f32_e32 v68, v68
	v_exp_f32_e32 v69, v69
	v_add_f32_e32 v182, v66, v182
	v_add_f32_e32 v182, v67, v182
	v_cvt_pk_bf16_f32 v137, v66, v67
	v_mfma_f32_32x32x16_bf16 v[0:15], v[132:135], v[156:159], v[0:15]
	ds_read_b64_tr_b16 v[156:157], v252 offset:42496
	ds_read_b64_tr_b16 v[158:159], v252 offset:44544
	v_exp_f32_e32 v70, v70
	v_exp_f32_e32 v71, v71
	v_add_f32_e32 v182, v68, v182
	v_add_f32_e32 v182, v69, v182
	v_cvt_pk_bf16_f32 v138, v68, v69
	v_cvt_pk_bf16_f32 v139, v70, v71
	v_add_f32_e32 v182, v70, v182
	v_add_f32_e32 v182, v71, v182
	v_mfma_f32_32x32x16_bf16 v[112:127], v[208:211], v[164:167], v[112:127]
	v_mfma_f32_32x32x16_bf16 v[96:111], v[212:215], v[164:167], v[96:111]
	v_mfma_f32_32x32x16_bf16 v[112:127], v[216:219], v[160:163], v[112:127]
	v_mfma_f32_32x32x16_bf16 v[96:111], v[220:223], v[160:163], v[96:111]
	s_setprio 1
	s_waitcnt lgkmcnt(4)
	v_mfma_f32_32x32x16_bf16 v[48:63], v[136:139], v[144:147], v[48:63]
	ds_read_b64_tr_b16 v[144:145], v252 offset:45056
	ds_read_b64_tr_b16 v[146:147], v252 offset:47104
	v_exp_f32_e32 v72, v72
	v_exp_f32_e32 v73, v73
	v_mfma_f32_32x32x16_bf16 v[32:47], v[136:139], v[148:151], v[32:47]
	ds_read_b64_tr_b16 v[148:149], v252 offset:45568
	ds_read_b64_tr_b16 v[150:151], v252 offset:47616
	v_exp_f32_e32 v74, v74
	v_exp_f32_e32 v75, v75
	v_add_f32_e32 v182, v72, v182
	v_add_f32_e32 v182, v73, v182
	v_cvt_pk_bf16_f32 v140, v72, v73
	s_waitcnt lgkmcnt(4)
	v_mfma_f32_32x32x16_bf16 v[16:31], v[136:139], v[152:155], v[16:31]
	ds_read_b64_tr_b16 v[152:153], v252 offset:46080
	ds_read_b64_tr_b16 v[154:155], v252 offset:48128
	v_exp_f32_e32 v76, v76
	v_exp_f32_e32 v77, v77
	v_add_f32_e32 v182, v74, v182
	v_add_f32_e32 v182, v75, v182
	v_cvt_pk_bf16_f32 v141, v74, v75
	v_mfma_f32_32x32x16_bf16 v[0:15], v[136:139], v[156:159], v[0:15]
	ds_read_b64_tr_b16 v[156:157], v252 offset:46592
	ds_read_b64_tr_b16 v[158:159], v252 offset:48640
	v_exp_f32_e32 v78, v78
	v_exp_f32_e32 v79, v79
	v_add_f32_e32 v182, v76, v182
	v_add_f32_e32 v182, v77, v182
	v_cvt_pk_bf16_f32 v142, v76, v77
	v_cvt_pk_bf16_f32 v143, v78, v79
	v_add_f32_e32 v182, v78, v182
	v_add_f32_e32 v182, v79, v182
	s_setprio 0
	s_waitcnt lgkmcnt(4)
	v_mfma_f32_32x32x16_bf16 v[48:63], v[140:143], v[144:147], v[48:63]
	v_exp_f32_e32 v112, v112
	v_exp_f32_e32 v113, v113
	v_mfma_f32_32x32x16_bf16 v[32:47], v[140:143], v[148:151], v[32:47]
	v_exp_f32_e32 v114, v114
	v_exp_f32_e32 v115, v115
	v_add_f32_e32 v182, v112, v182
	v_add_f32_e32 v182, v113, v182
	v_cvt_pk_bf16_f32 v128, v112, v113
	s_waitcnt lgkmcnt(0)
	v_mfma_f32_32x32x16_bf16 v[16:31], v[140:143], v[152:155], v[16:31]
	v_exp_f32_e32 v116, v116
	v_exp_f32_e32 v117, v117
	v_add_f32_e32 v182, v114, v182
	v_add_f32_e32 v182, v115, v182
	v_cvt_pk_bf16_f32 v129, v114, v115
	v_mfma_f32_32x32x16_bf16 v[0:15], v[140:143], v[156:159], v[0:15]
	v_exp_f32_e32 v118, v118
	v_exp_f32_e32 v119, v119
	v_add_f32_e32 v182, v116, v182
	v_add_f32_e32 v182, v117, v182
	v_cvt_pk_bf16_f32 v130, v116, v117
	v_cvt_pk_bf16_f32 v131, v118, v119
	v_add_f32_e32 v182, v118, v182
	v_add_f32_e32 v182, v119, v182
	s_add_i32 s54, s54, 1
	s_cmp_ge_i32 s54, s62
	s_cbranch_scc1 .Lsym_last3_x
	s_waitcnt vmcnt(0)
	s_barrier
	ds_read_b128 v[192:195], v178 offset:0
	ds_read_b128 v[196:199], v178 offset:8192
	ds_read_b128 v[200:203], v179 offset:0
	ds_read_b128 v[204:207], v179 offset:8192
	ds_read_b128 v[208:211], v180 offset:0
	ds_read_b128 v[212:215], v180 offset:8192
	ds_read_b128 v[216:219], v181 offset:0
	ds_read_b128 v[220:223], v181 offset:8192
	s_add_i32 s53, s54, 2
	s_cmp_le_i32 s53, s62
	s_cbranch_scc0 .Lsym_nostage_xs3
	s_add_i32 m0, s25, 0x4000
	s_add_u32 s60, s56, 0x70000
	s_addc_u32 s61, s57, 0
	global_load_lds_dwordx4 v176, s[56:57]
	s_add_i32 m0, s24, 0x4000
	s_nop 0
	global_load_lds_dwordx4 v188, s[56:57]
	s_add_i32 m0, s25, 0x6000
	s_add_u32 s56, s56, 0xe0000
	s_addc_u32 s57, s57, 0
	global_load_lds_dwordx4 v176, s[60:61]
	s_add_i32 m0, s24, 0x6000
	s_nop 0
	global_load_lds_dwordx4 v188, s[60:61]

; #define SBAR() __builtin_amdgcn_sched_barrier(0)
; template <int KS> __device__ __forceinline__ void pv_ks(f32x16* o, int vb, bf16x8 pa) {
;     const s16x4 l0 = tr_read<v_rd_off(0, KS, 0)>(vb), h0 = tr_read<v_rd_off(0, KS, 1)>(vb), l1 = tr_read<v_rd_off(1, KS, 0)>(vb), h1 = tr_read<v_rd_off(1, KS, 1)>(vb);
;     const s16x4 l2 = tr_read<v_rd_off(2, KS, 0)>(vb), h2 = tr_read<v_rd_off(2, KS, 1)>(vb), l3 = tr_read<v_rd_off(3, KS, 0)>(vb), h3 = tr_read<v_rd_off(3, KS, 1)>(vb);
;     ...
;     asm volatile("s_waitcnt lgkmcnt(6)" ::: "memory"); SBAR();
;     o[0] = __builtin_amdgcn_mfma_f32_32x32x16_bf16(pa, PK(l0, h0), o[0], 0, 0, 0);
;     asm volatile("s_waitcnt lgkmcnt(4)" ::: "memory"); SBAR();
;     o[1] = __builtin_amdgcn_mfma_f32_32x32x16_bf16(pa, PK(l1, h1), o[1], 0, 0, 0);
;     asm volatile("s_waitcnt lgkmcnt(2)" ::: "memory"); SBAR();
;     o[2] = __builtin_amdgcn_mfma_f32_32x32x16_bf16(pa, PK(l2, h2), o[2], 0, 0, 0);
;     asm volatile("s_waitcnt lgkmcnt(0)" ::: "memory"); SBAR();
;     o[3] = __builtin_amdgcn_mfma_f32_32x32x16_bf16(pa, PK(l3, h3), o[3], 0, 0, 0);
;     ...
; }
; __device__ __forceinline__ void pv_d0(f32x16* o, int vb, bf16x8 pa0, bf16x8 pa1, bf16x8 pa2, bf16x8 pa3) {
;     __builtin_amdgcn_s_setprio(1);
;     pv_ks<0>(o, vb, pa0); pv_ks<1>(o, vb, pa1); pv_ks<2>(o, vb, pa2); pv_ks<3>(o, vb, pa3);
;     __builtin_amdgcn_s_setprio(0);
; }
; __device__ __forceinline__ void exp_half(f32x16& p) {
; #pragma unroll
;     for (int r = 0; r < 16; ++r) p[r] = __builtin_amdgcn_exp2f(p[r]);
; }
; __device__ __forceinline__ void pack_p(const f32x16& p0, const f32x16& p1, float& l_reg, bf16x8& pa0, bf16x8& pa1, bf16x8& pa2, bf16x8& pa3) {
;     float ps = 0;
; #pragma unroll
;     for (int r = 0; r < 16; ++r) ps += p0[r];
; #pragma unroll
;     for (int r = 0; r < 16; ++r) ps += p1[r];
;     l_reg += ps;
;     ...
;     PK4(p0, 0, pa0); PK4(p0, 8, pa1); PK4(p1, 0, pa2); PK4(p1, 8, pa3);
;     ...
; }
; __device__ __forceinline__ void diff_unit(const DiffArgs& A, int b, int h, int qb, char* lds, int wv) {
;     ...
;         for (int j = 1; j + 1 < NT; j += 2) {
;             STAGE(j + 1);
;             SBAR(); BIAS(pB0, pB1, j); qkt<4>(pB0, pB1, K_lds + SLOT(j), qr, r32p, hip, colB0);
;             exp_half(pA1); pack_p(pA0, pA1, l_reg, pa0, pa1, pa2, pa3); SBAR();
;             pv_d0(o, vb0 + SLOT(j - 1), pa0, pa1, pa2, pa3); exp_half(pB0);
;             ENDI();
;             STAGE(j + 2);
.Lsym_biasdone_xs3:
	s_add_i32 s55, s55, 64
	v_add_f32_e32 v183, 0xc2800000, v183
	ds_read_b64_tr_b16 v[144:145], v252 offset:49152
	ds_read_b64_tr_b16 v[146:147], v252 offset:51200
	ds_read_b64_tr_b16 v[148:149], v252 offset:49664
	ds_read_b64_tr_b16 v[150:151], v252 offset:51712
	ds_read_b64_tr_b16 v[152:153], v252 offset:50176
	ds_read_b64_tr_b16 v[154:155], v252 offset:52224
	ds_read_b64_tr_b16 v[156:157], v252 offset:50688
	ds_read_b64_tr_b16 v[158:159], v252 offset:52736
	s_setprio 1
	s_waitcnt lgkmcnt(4)
	v_mfma_f32_32x32x16_bf16 v[48:63], v[128:131], v[144:147], v[48:63]
	ds_read_b64_tr_b16 v[144:145], v252 offset:53248
	ds_read_b64_tr_b16 v[146:147], v252 offset:55296
	v_exp_f32_e32 v120, v120
	v_exp_f32_e32 v121, v121
	v_mfma_f32_32x32x16_bf16 v[32:47], v[128:131], v[148:151], v[32:47]
	ds_read_b64_tr_b16 v[148:149], v252 offset:53760
	ds_read_b64_tr_b16 v[150:151], v252 offset:55808
	v_exp_f32_e32 v122, v122
	v_exp_f32_e32 v123, v123
	v_add_f32_e32 v182, v120, v182
	v_add_f32_e32 v182, v121, v182
	v_cvt_pk_bf16_f32 v132, v120, v121
	s_waitcnt lgkmcnt(4)
	v_mfma_f32_32x32x16_bf16 v[16:31], v[128:131], v[152:155], v[16:31]
	ds_read_b64_tr_b16 v[152:153], v252 offset:54272
	ds_read_b64_tr_b16 v[154:155], v252 offset:56320
	v_exp_f32_e32 v124, v124
	v_exp_f32_e32 v125, v125
	v_add_f32_e32 v182, v122, v182
	v_add_f32_e32 v182, v123, v182
	v_cvt_pk_bf16_f32 v133, v122, v123
	v_mfma_f32_32x32x16_bf16 v[0:15], v[128:131], v[156:159], v[0:15]
	ds_read_b64_tr_b16 v[156:157], v252 offset:54784
	ds_read_b64_tr_b16 v[158:159], v252 offset:56832
	v_exp_f32_e32 v126, v126
	v_exp_f32_e32 v127, v127
	v_add_f32_e32 v182, v124, v182
	v_add_f32_e32 v182, v125, v182
	v_cvt_pk_bf16_f32 v134, v124, v125
	v_cvt_pk_bf16_f32 v135, v126, v127
	v_add_f32_e32 v182, v126, v182
	v_add_f32_e32 v182, v127, v182
	v_mfma_f32_32x32x16_bf16 v[80:95], v[192:195], v[172:175], v[80:95]
	v_mfma_f32_32x32x16_bf16 v[64:79], v[196:199], v[172:175], v[64:79]
	v_mfma_f32_32x32x16_bf16 v[80:95], v[200:203], v[168:171], v[80:95]
	v_mfma_f32_32x32x16_bf16 v[64:79], v[204:207], v[168:171], v[64:79]
	s_setprio 0
	s_waitcnt lgkmcnt(4)
	v_mfma_f32_32x32x16_bf16 v[48:63], v[132:135], v[144:147], v[48:63]
	ds_read_b64_tr_b16 v[144:145], v252 offset:57344
	ds_read_b64_tr_b16 v[146:147], v252 offset:59392
	v_exp_f32_e32 v96, v96
	v_exp_f32_e32 v97, v97
	v_mfma_f32_32x32x16_bf16 v[32:47], v[132:135], v[148:151], v[32:47]
	ds_read_b64_tr_b16 v[148:149], v252 offset:57856
	ds_read_b64_tr_b16 v[150:151], v252 offset:59904
	v_exp_f32_e32 v98, v98
	v_exp_f32_e32 v99, v99
	v_add_f32_e32 v182, v96, v182
	v_add_f32_e32 v182, v97, v182
	v_cvt_pk_bf16_f32 v136, v96, v97
	s_waitcnt lgkmcnt(4)
	v_mfma_f32_32x32x16_bf16 v[16:31], v[132:135], v[152:155], v[16:31]
	ds_read_b64_tr_b16 v[152:153], v252 offset:58368
	ds_read_b64_tr_b16 v[154:155], v252 offset:60416
	v_exp_f32_e32 v100, v100
	v_exp_f32_e32 v101, v101
	v_add_f32_e32 v182, v98, v182
	v_add_f32_e32 v182, v99, v182
	v_cvt_pk_bf16_f32 v137, v98, v99
	v_mfma_f32_32x32x16_bf16 v[0:15], v[132:135], v[156:159], v[0:15]
	ds_read_b64_tr_b16 v[156:157], v252 offset:58880
	ds_read_b64_tr_b16 v[158:159], v252 offset:60928
	v_exp_f32_e32 v102, v102
	v_exp_f32_e32 v103, v103
	v_add_f32_e32 v182, v100, v182
	v_add_f32_e32 v182, v101, v182
	v_cvt_pk_bf16_f32 v138, v100, v101
	v_cvt_pk_bf16_f32 v139, v102, v103
	v_add_f32_e32 v182, v102, v182
	v_add_f32_e32 v182, v103, v182
	v_mfma_f32_32x32x16_bf16 v[80:95], v[208:211], v[164:167], v[80:95]
	v_mfma_f32_32x32x16_bf16 v[64:79], v[212:215], v[164:167], v[64:79]
	v_mfma_f32_32x32x16_bf16 v[80:95], v[216:219], v[160:163], v[80:95]
	v_mfma_f32_32x32x16_bf16 v[64:79], v[220:223], v[160:163], v[64:79]
	s_setprio 1
	s_waitcnt lgkmcnt(4)
	v_mfma_f32_32x32x16_bf16 v[48:63], v[136:139], v[144:147], v[48:63]
	ds_read_b64_tr_b16 v[144:145], v252 offset:61440
	ds_read_b64_tr_b16 v[146:147], v252 offset:63488
	v_exp_f32_e32 v104, v104
	v_exp_f32_e32 v105, v105
	v_mfma_f32_32x32x16_bf16 v[32:47], v[136:139], v[148:151], v[32:47]
	ds_read_b64_tr_b16 v[148:149], v252 offset:61952
	ds_read_b64_tr_b16 v[150:151], v252 offset:64000
	v_exp_f32_e32 v106, v106
	v_exp_f32_e32 v107, v107
	v_add_f32_e32 v182, v104, v182
	v_add_f32_e32 v182, v105, v182
	v_cvt_pk_bf16_f32 v140, v104, v105
	s_waitcnt lgkmcnt(4)
	v_mfma_f32_32x32x16_bf16 v[16:31], v[136:139], v[152:155], v[16:31]
	ds_read_b64_tr_b16 v[152:153], v252 offset:62464
	ds_read_b64_tr_b16 v[154:155], v252 offset:64512
	v_exp_f32_e32 v108, v108
	v_exp_f32_e32 v109, v109
	v_add_f32_e32 v182, v106, v182
	v_add_f32_e32 v182, v107, v182
	v_cvt_pk_bf16_f32 v141, v106, v107
	v_mfma_f32_32x32x16_bf16 v[0:15], v[136:139], v[156:159], v[0:15]
	ds_read_b64_tr_b16 v[156:157], v252 offset:62976
	ds_read_b64_tr_b16 v[158:159], v252 offset:65024
	v_exp_f32_e32 v110, v110
	v_exp_f32_e32 v111, v111
	v_add_f32_e32 v182, v108, v182
	v_add_f32_e32 v182, v109, v182
	v_cvt_pk_bf16_f32 v142, v108, v109
	v_cvt_pk_bf16_f32 v143, v110, v111
	v_add_f32_e32 v182, v110, v182
	v_add_f32_e32 v182, v111, v182
	s_setprio 0
	s_waitcnt lgkmcnt(4)
	v_mfma_f32_32x32x16_bf16 v[48:63], v[140:143], v[144:147], v[48:63]
	v_exp_f32_e32 v80, v80
	v_exp_f32_e32 v81, v81
	v_mfma_f32_32x32x16_bf16 v[32:47], v[140:143], v[148:151], v[32:47]
	v_exp_f32_e32 v82, v82
	v_exp_f32_e32 v83, v83
	v_add_f32_e32 v182, v80, v182
	v_add_f32_e32 v182, v81, v182
	v_cvt_pk_bf16_f32 v128, v80, v81
	s_waitcnt lgkmcnt(0)
	v_mfma_f32_32x32x16_bf16 v[16:31], v[140:143], v[152:155], v[16:31]
	v_exp_f32_e32 v84, v84
	v_exp_f32_e32 v85, v85
	v_add_f32_e32 v182, v82, v182
	v_add_f32_e32 v182, v83, v182
	v_cvt_pk_bf16_f32 v129, v82, v83
	v_mfma_f32_32x32x16_bf16 v[0:15], v[140:143], v[156:159], v[0:15]
	v_exp_f32_e32 v86, v86
	v_exp_f32_e32 v87, v87
	v_add_f32_e32 v182, v84, v182
	v_add_f32_e32 v182, v85, v182
	v_cvt_pk_bf16_f32 v130, v84, v85
	v_cvt_pk_bf16_f32 v131, v86, v87
	v_add_f32_e32 v182, v86, v182
	v_add_f32_e32 v182, v87, v182
	s_add_i32 s54, s54, 1
	s_branch .Lsym_loop_x
; #define SBAR() __builtin_amdgcn_sched_barrier(0)
; #define PK4(P, BASE, OUT) do { u32x4 w = {cvtpk(P[BASE + 0], P[BASE + 1]), cvtpk(P[BASE + 2], P[BASE + 3]), cvtpk(P[BASE + 4], P[BASE + 5]), cvtpk(P[BASE + 6], P[BASE + 7])}; \
;     OUT = *reinterpret_cast<bf16x8*>(&w); } while (0)
; template <int KS> __device__ __forceinline__ void pv_ks(f32x16* o, int vb, bf16x8 pa) {
;     const s16x4 l0 = tr_read<v_rd_off(0, KS, 0)>(vb), h0 = tr_read<v_rd_off(0, KS, 1)>(vb), l1 = tr_read<v_rd_off(1, KS, 0)>(vb), h1 = tr_read<v_rd_off(1, KS, 1)>(vb);
;     const s16x4 l2 = tr_read<v_rd_off(2, KS, 0)>(vb), h2 = tr_read<v_rd_off(2, KS, 1)>(vb), l3 = tr_read<v_rd_off(3, KS, 0)>(vb), h3 = tr_read<v_rd_off(3, KS, 1)>(vb);
;     ...
;     asm volatile("s_waitcnt lgkmcnt(6)" ::: "memory"); SBAR();
;     o[0] = __builtin_amdgcn_mfma_f32_32x32x16_bf16(pa, PK(l0, h0), o[0], 0, 0, 0);
;     asm volatile("s_waitcnt lgkmcnt(4)" ::: "memory"); SBAR();
;     o[1] = __builtin_amdgcn_mfma_f32_32x32x16_bf16(pa, PK(l1, h1), o[1], 0, 0, 0);
;     asm volatile("s_waitcnt lgkmcnt(2)" ::: "memory"); SBAR();
;     o[2] = __builtin_amdgcn_mfma_f32_32x32x16_bf16(pa, PK(l2, h2), o[2], 0, 0, 0);
;     asm volatile("s_waitcnt lgkmcnt(0)" ::: "memory"); SBAR();
;     o[3] = __builtin_amdgcn_mfma_f32_32x32x16_bf16(pa, PK(l3, h3), o[3], 0, 0, 0);
;     ...
; }
; __device__ __forceinline__ void pv_d0(f32x16* o, int vb, bf16x8 pa0, bf16x8 pa1, bf16x8 pa2, bf16x8 pa3) {
;     __builtin_amdgcn_s_setprio(1);
;     pv_ks<0>(o, vb, pa0); pv_ks<1>(o, vb, pa1); pv_ks<2>(o, vb, pa2); pv_ks<3>(o, vb, pa3);
;     __builtin_amdgcn_s_setprio(0);
; }
; __device__ __forceinline__ void exp_half(f32x16& p) {
; #pragma unroll
;     for (int r = 0; r < 16; ++r) p[r] = __builtin_amdgcn_exp2f(p[r]);
; }
; __device__ __forceinline__ void pack_p(const f32x16& p0, const f32x16& p1, float& l_reg, bf16x8& pa0, bf16x8& pa1, bf16x8& pa2, bf16x8& pa3) {
;     float ps = 0;
; #pragma unroll
;     for (int r = 0; r < 16; ++r) ps += p0[r];
; #pragma unroll
;     for (int r = 0; r < 16; ++r) ps += p1[r];
;     l_reg += ps;
;     ...
;     PK4(p0, 0, pa0); PK4(p0, 8, pa1); PK4(p1, 0, pa2); PK4(p1, 8, pa3);
;     ...
; }
.Lsym_last1_x:
	s_waitcnt vmcnt(0)
	s_barrier
	ds_read_b64_tr_b16 v[144:145], v252 offset:16384
	ds_read_b64_tr_b16 v[146:147], v252 offset:18432
	ds_read_b64_tr_b16 v[148:149], v252 offset:16896
	ds_read_b64_tr_b16 v[150:151], v252 offset:18944
	ds_read_b64_tr_b16 v[152:153], v252 offset:17408
	ds_read_b64_tr_b16 v[154:155], v252 offset:19456
	ds_read_b64_tr_b16 v[156:157], v252 offset:17920
	ds_read_b64_tr_b16 v[158:159], v252 offset:19968
	s_setprio 1
	s_waitcnt lgkmcnt(4)
	v_mfma_f32_32x32x16_bf16 v[48:63], v[128:131], v[144:147], v[48:63]
	ds_read_b64_tr_b16 v[144:145], v252 offset:20480
	ds_read_b64_tr_b16 v[146:147], v252 offset:22528
	v_exp_f32_e32 v120, v120
	v_exp_f32_e32 v121, v121
	v_mfma_f32_32x32x16_bf16 v[32:47], v[128:131], v[148:151], v[32:47]
	ds_read_b64_tr_b16 v[148:149], v252 offset:20992
	ds_read_b64_tr_b16 v[150:151], v252 offset:23040
	v_exp_f32_e32 v122, v122
	v_exp_f32_e32 v123, v123
	v_add_f32_e32 v182, v120, v182
	v_add_f32_e32 v182, v121, v182
	v_cvt_pk_bf16_f32 v132, v120, v121
	s_waitcnt lgkmcnt(4)
	v_mfma_f32_32x32x16_bf16 v[16:31], v[128:131], v[152:155], v[16:31]
	ds_read_b64_tr_b16 v[152:153], v252 offset:21504
	ds_read_b64_tr_b16 v[154:155], v252 offset:23552
	v_exp_f32_e32 v124, v124
	v_exp_f32_e32 v125, v125
	v_add_f32_e32 v182, v122, v182
	v_add_f32_e32 v182, v123, v182
	v_cvt_pk_bf16_f32 v133, v122, v123
	v_mfma_f32_32x32x16_bf16 v[0:15], v[128:131], v[156:159], v[0:15]
	ds_read_b64_tr_b16 v[156:157], v252 offset:22016
	ds_read_b64_tr_b16 v[158:159], v252 offset:24064
	v_exp_f32_e32 v126, v126
	v_exp_f32_e32 v127, v127
	v_add_f32_e32 v182, v124, v182
	v_add_f32_e32 v182, v125, v182
	v_cvt_pk_bf16_f32 v134, v124, v125
	v_cvt_pk_bf16_f32 v135, v126, v127
	v_add_f32_e32 v182, v126, v182
	v_add_f32_e32 v182, v127, v182
	s_setprio 0
	s_waitcnt lgkmcnt(4)
	v_mfma_f32_32x32x16_bf16 v[48:63], v[132:135], v[144:147], v[48:63]
	ds_read_b64_tr_b16 v[144:145], v252 offset:24576
	ds_read_b64_tr_b16 v[146:147], v252 offset:26624
	v_exp_f32_e32 v96, v96
	v_exp_f32_e32 v97, v97
	v_mfma_f32_32x32x16_bf16 v[32:47], v[132:135], v[148:151], v[32:47]
	ds_read_b64_tr_b16 v[148:149], v252 offset:25088
	ds_read_b64_tr_b16 v[150:151], v252 offset:27136
	v_exp_f32_e32 v98, v98
	v_exp_f32_e32 v99, v99
	v_add_f32_e32 v182, v96, v182
	v_add_f32_e32 v182, v97, v182
	v_cvt_pk_bf16_f32 v136, v96, v97
	s_waitcnt lgkmcnt(4)
	v_mfma_f32_32x32x16_bf16 v[16:31], v[132:135], v[152:155], v[16:31]
	ds_read_b64_tr_b16 v[152:153], v252 offset:25600
	ds_read_b64_tr_b16 v[154:155], v252 offset:27648
	v_exp_f32_e32 v100, v100
	v_exp_f32_e32 v101, v101
	v_add_f32_e32 v182, v98, v182
	v_add_f32_e32 v182, v99, v182
	v_cvt_pk_bf16_f32 v137, v98, v99
	v_mfma_f32_32x32x16_bf16 v[0:15], v[132:135], v[156:159], v[0:15]
	ds_read_b64_tr_b16 v[156:157], v252 offset:26112
	ds_read_b64_tr_b16 v[158:159], v252 offset:28160
	v_exp_f32_e32 v102, v102
	v_exp_f32_e32 v103, v103
	v_add_f32_e32 v182, v100, v182
	v_add_f32_e32 v182, v101, v182
	v_cvt_pk_bf16_f32 v138, v100, v101
	v_cvt_pk_bf16_f32 v139, v102, v103
	v_add_f32_e32 v182, v102, v182
	v_add_f32_e32 v182, v103, v182
	s_setprio 1
	s_waitcnt lgkmcnt(4)
	v_mfma_f32_32x32x16_bf16 v[48:63], v[136:139], v[144:147], v[48:63]
	ds_read_b64_tr_b16 v[144:145], v252 offset:28672
	ds_read_b64_tr_b16 v[146:147], v252 offset:30720
	v_exp_f32_e32 v104, v104
	v_exp_f32_e32 v105, v105
	v_mfma_f32_32x32x16_bf16 v[32:47], v[136:139], v[148:151], v[32:47]
	ds_read_b64_tr_b16 v[148:149], v252 offset:29184
	ds_read_b64_tr_b16 v[150:151], v252 offset:31232
	v_exp_f32_e32 v106, v106
	v_exp_f32_e32 v107, v107
	v_add_f32_e32 v182, v104, v182
	v_add_f32_e32 v182, v105, v182
	v_cvt_pk_bf16_f32 v140, v104, v105
	s_waitcnt lgkmcnt(4)
	v_mfma_f32_32x32x16_bf16 v[16:31], v[136:139], v[152:155], v[16:31]
	ds_read_b64_tr_b16 v[152:153], v252 offset:29696
	ds_read_b64_tr_b16 v[154:155], v252 offset:31744
	v_exp_f32_e32 v108, v108
	v_exp_f32_e32 v109, v109
	v_add_f32_e32 v182, v106, v182
	v_add_f32_e32 v182, v107, v182
	v_cvt_pk_bf16_f32 v141, v106, v107
	v_mfma_f32_32x32x16_bf16 v[0:15], v[136:139], v[156:159], v[0:15]
	ds_read_b64_tr_b16 v[156:157], v252 offset:30208
	ds_read_b64_tr_b16 v[158:159], v252 offset:32256
	v_exp_f32_e32 v110, v110
	v_exp_f32_e32 v111, v111
	v_add_f32_e32 v182, v108, v182
	v_add_f32_e32 v182, v109, v182
	v_cvt_pk_bf16_f32 v142, v108, v109
	v_cvt_pk_bf16_f32 v143, v110, v111
	v_add_f32_e32 v182, v110, v182
	v_add_f32_e32 v182, v111, v182
	s_setprio 0
	s_waitcnt lgkmcnt(4)
	v_mfma_f32_32x32x16_bf16 v[48:63], v[140:143], v[144:147], v[48:63]
	v_mfma_f32_32x32x16_bf16 v[32:47], v[140:143], v[148:151], v[32:47]
	s_waitcnt lgkmcnt(0)
	v_mfma_f32_32x32x16_bf16 v[16:31], v[140:143], v[152:155], v[16:31]
	v_mfma_f32_32x32x16_bf16 v[0:15], v[140:143], v[156:159], v[0:15]
	s_branch .Lsym_done
; #define SBAR() __builtin_amdgcn_sched_barrier(0)
; #define PK4(P, BASE, OUT) do { u32x4 w = {cvtpk(P[BASE + 0], P[BASE + 1]), cvtpk(P[BASE + 2], P[BASE + 3]), cvtpk(P[BASE + 4], P[BASE + 5]), cvtpk(P[BASE + 6], P[BASE + 7])}; \
;     OUT = *reinterpret_cast<bf16x8*>(&w); } while (0)
; template <int KS> __device__ __forceinline__ void pv_ks(f32x16* o, int vb, bf16x8 pa) {
;     const s16x4 l0 = tr_read<v_rd_off(0, KS, 0)>(vb), h0 = tr_read<v_rd_off(0, KS, 1)>(vb), l1 = tr_read<v_rd_off(1, KS, 0)>(vb), h1 = tr_read<v_rd_off(1, KS, 1)>(vb);
;     const s16x4 l2 = tr_read<v_rd_off(2, KS, 0)>(vb), h2 = tr_read<v_rd_off(2, KS, 1)>(vb), l3 = tr_read<v_rd_off(3, KS, 0)>(vb), h3 = tr_read<v_rd_off(3, KS, 1)>(vb);
;     ...
;     asm volatile("s_waitcnt lgkmcnt(6)" ::: "memory"); SBAR();
;     o[0] = __builtin_amdgcn_mfma_f32_32x32x16_bf16(pa, PK(l0, h0), o[0], 0, 0, 0);
;     asm volatile("s_waitcnt lgkmcnt(4)" ::: "memory"); SBAR();
;     o[1] = __builtin_amdgcn_mfma_f32_32x32x16_bf16(pa, PK(l1, h1), o[1], 0, 0, 0);
;     asm volatile("s_waitcnt lgkmcnt(2)" ::: "memory"); SBAR();
;     o[2] = __builtin_amdgcn_mfma_f32_32x32x16_bf16(pa, PK(l2, h2), o[2], 0, 0, 0);
;     asm volatile("s_waitcnt lgkmcnt(0)" ::: "memory"); SBAR();
;     o[3] = __builtin_amdgcn_mfma_f32_32x32x16_bf16(pa, PK(l3, h3), o[3], 0, 0, 0);
;     ...
; }
; __device__ __forceinline__ void pv_d0(f32x16* o, int vb, bf16x8 pa0, bf16x8 pa1, bf16x8 pa2, bf16x8 pa3) {
;     __builtin_amdgcn_s_setprio(1);
;     pv_ks<0>(o, vb, pa0); pv_ks<1>(o, vb, pa1); pv_ks<2>(o, vb, pa2); pv_ks<3>(o, vb, pa3);
;     __builtin_amdgcn_s_setprio(0);
; }
; __device__ __forceinline__ void exp_half(f32x16& p) {
; #pragma unroll
;     for (int r = 0; r < 16; ++r) p[r] = __builtin_amdgcn_exp2f(p[r]);
; }
; __device__ __forceinline__ void pack_p(const f32x16& p0, const f32x16& p1, float& l_reg, bf16x8& pa0, bf16x8& pa1, bf16x8& pa2, bf16x8& pa3) {
;     float ps = 0;
; #pragma unroll
;     for (int r = 0; r < 16; ++r) ps += p0[r];
; #pragma unroll
;     for (int r = 0; r < 16; ++r) ps += p1[r];
;     l_reg += ps;
;     ...
;     PK4(p0, 0, pa0); PK4(p0, 8, pa1); PK4(p1, 0, pa2); PK4(p1, 8, pa3);
;     ...
; }
.Lsym_last3_x:
	s_waitcnt vmcnt(0)
	s_barrier
	ds_read_b64_tr_b16 v[144:145], v252 offset:49152
	ds_read_b64_tr_b16 v[146:147], v252 offset:51200
	ds_read_b64_tr_b16 v[148:149], v252 offset:49664
	ds_read_b64_tr_b16 v[150:151], v252 offset:51712
	ds_read_b64_tr_b16 v[152:153], v252 offset:50176
	ds_read_b64_tr_b16 v[154:155], v252 offset:52224
	ds_read_b64_tr_b16 v[156:157], v252 offset:50688
	ds_read_b64_tr_b16 v[158:159], v252 offset:52736
	s_setprio 1
	s_waitcnt lgkmcnt(4)
	v_mfma_f32_32x32x16_bf16 v[48:63], v[128:131], v[144:147], v[48:63]
	ds_read_b64_tr_b16 v[144:145], v252 offset:53248
	ds_read_b64_tr_b16 v[146:147], v252 offset:55296
	v_exp_f32_e32 v120, v120
	v_exp_f32_e32 v121, v121
	v_mfma_f32_32x32x16_bf16 v[32:47], v[128:131], v[148:151], v[32:47]
	ds_read_b64_tr_b16 v[148:149], v252 offset:53760
	ds_read_b64_tr_b16 v[150:151], v252 offset:55808
	v_exp_f32_e32 v122, v122
	v_exp_f32_e32 v123, v123
	v_add_f32_e32 v182, v120, v182
	v_add_f32_e32 v182, v121, v182
	v_cvt_pk_bf16_f32 v132, v120, v121
	s_waitcnt lgkmcnt(4)
	v_mfma_f32_32x32x16_bf16 v[16:31], v[128:131], v[152:155], v[16:31]
	ds_read_b64_tr_b16 v[152:153], v252 offset:54272
	ds_read_b64_tr_b16 v[154:155], v252 offset:56320
	v_exp_f32_e32 v124, v124
	v_exp_f32_e32 v125, v125
	v_add_f32_e32 v182, v122, v182
	v_add_f32_e32 v182, v123, v182
	v_cvt_pk_bf16_f32 v133, v122, v123
	v_mfma_f32_32x32x16_bf16 v[0:15], v[128:131], v[156:159], v[0:15]
	ds_read_b64_tr_b16 v[156:157], v252 offset:54784
	ds_read_b64_tr_b16 v[158:159], v252 offset:56832
	v_exp_f32_e32 v126, v126
	v_exp_f32_e32 v127, v127
	v_add_f32_e32 v182, v124, v182
	v_add_f32_e32 v182, v125, v182
	v_cvt_pk_bf16_f32 v134, v124, v125
	v_cvt_pk_bf16_f32 v135, v126, v127
	v_add_f32_e32 v182, v126, v182
	v_add_f32_e32 v182, v127, v182
	s_setprio 0
	s_waitcnt lgkmcnt(4)
	v_mfma_f32_32x32x16_bf16 v[48:63], v[132:135], v[144:147], v[48:63]
	ds_read_b64_tr_b16 v[144:145], v252 offset:57344
	ds_read_b64_tr_b16 v[146:147], v252 offset:59392
	v_exp_f32_e32 v96, v96
	v_exp_f32_e32 v97, v97
	v_mfma_f32_32x32x16_bf16 v[32:47], v[132:135], v[148:151], v[32:47]
	ds_read_b64_tr_b16 v[148:149], v252 offset:57856
	ds_read_b64_tr_b16 v[150:151], v252 offset:59904
	v_exp_f32_e32 v98, v98
	v_exp_f32_e32 v99, v99
	v_add_f32_e32 v182, v96, v182
	v_add_f32_e32 v182, v97, v182
	v_cvt_pk_bf16_f32 v136, v96, v97
	s_waitcnt lgkmcnt(4)
	v_mfma_f32_32x32x16_bf16 v[16:31], v[132:135], v[152:155], v[16:31]
	ds_read_b64_tr_b16 v[152:153], v252 offset:58368
	ds_read_b64_tr_b16 v[154:155], v252 offset:60416
	v_exp_f32_e32 v100, v100
	v_exp_f32_e32 v101, v101
	v_add_f32_e32 v182, v98, v182
	v_add_f32_e32 v182, v99, v182
	v_cvt_pk_bf16_f32 v137, v98, v99
	v_mfma_f32_32x32x16_bf16 v[0:15], v[132:135], v[156:159], v[0:15]
	ds_read_b64_tr_b16 v[156:157], v252 offset:58880
	ds_read_b64_tr_b16 v[158:159], v252 offset:60928
	v_exp_f32_e32 v102, v102
	v_exp_f32_e32 v103, v103
	v_add_f32_e32 v182, v100, v182
	v_add_f32_e32 v182, v101, v182
	v_cvt_pk_bf16_f32 v138, v100, v101
	v_cvt_pk_bf16_f32 v139, v102, v103
	v_add_f32_e32 v182, v102, v182
	v_add_f32_e32 v182, v103, v182
	s_setprio 1
	s_waitcnt lgkmcnt(4)
	v_mfma_f32_32x32x16_bf16 v[48:63], v[136:139], v[144:147], v[48:63]
	ds_read_b64_tr_b16 v[144:145], v252 offset:61440
	ds_read_b64_tr_b16 v[146:147], v252 offset:63488
	v_exp_f32_e32 v104, v104
	v_exp_f32_e32 v105, v105
	v_mfma_f32_32x32x16_bf16 v[32:47], v[136:139], v[148:151], v[32:47]
	ds_read_b64_tr_b16 v[148:149], v252 offset:61952
	ds_read_b64_tr_b16 v[150:151], v252 offset:64000
	v_exp_f32_e32 v106, v106
	v_exp_f32_e32 v107, v107
	v_add_f32_e32 v182, v104, v182
	v_add_f32_e32 v182, v105, v182
	v_cvt_pk_bf16_f32 v140, v104, v105
	s_waitcnt lgkmcnt(4)
	v_mfma_f32_32x32x16_bf16 v[16:31], v[136:139], v[152:155], v[16:31]
	ds_read_b64_tr_b16 v[152:153], v252 offset:62464
	ds_read_b64_tr_b16 v[154:155], v252 offset:64512
	v_exp_f32_e32 v108, v108
	v_exp_f32_e32 v109, v109
	v_add_f32_e32 v182, v106, v182
	v_add_f32_e32 v182, v107, v182
	v_cvt_pk_bf16_f32 v141, v106, v107
	v_mfma_f32_32x32x16_bf16 v[0:15], v[136:139], v[156:159], v[0:15]
	ds_read_b64_tr_b16 v[156:157], v252 offset:62976
	ds_read_b64_tr_b16 v[158:159], v252 offset:65024
	v_exp_f32_e32 v110, v110
	v_exp_f32_e32 v111, v111
	v_add_f32_e32 v182, v108, v182
	v_add_f32_e32 v182, v109, v182
	v_cvt_pk_bf16_f32 v142, v108, v109
	v_cvt_pk_bf16_f32 v143, v110, v111
	v_add_f32_e32 v182, v110, v182
	v_add_f32_e32 v182, v111, v182
	s_setprio 0
	s_waitcnt lgkmcnt(4)
	v_mfma_f32_32x32x16_bf16 v[48:63], v[140:143], v[144:147], v[48:63]
	v_mfma_f32_32x32x16_bf16 v[32:47], v[140:143], v[148:151], v[32:47]
	s_waitcnt lgkmcnt(0)
	v_mfma_f32_32x32x16_bf16 v[16:31], v[140:143], v[152:155], v[16:31]
	v_mfma_f32_32x32x16_bf16 v[0:15], v[140:143], v[156:159], v[0:15]
	s_branch .Lsym_done

; template <int KS> __device__ __forceinline__ void pv_ks(f32x16* o, int vb, bf16x8 pa) {
;     const s16x4 l0 = tr_read<v_rd_off(0, KS, 0)>(vb), h0 = tr_read<v_rd_off(0, KS, 1)>(vb), l1 = tr_read<v_rd_off(1, KS, 0)>(vb), h1 = tr_read<v_rd_off(1, KS, 1)>(vb);
;     const s16x4 l2 = tr_read<v_rd_off(2, KS, 0)>(vb), h2 = tr_read<v_rd_off(2, KS, 1)>(vb), l3 = tr_read<v_rd_off(3, KS, 0)>(vb), h3 = tr_read<v_rd_off(3, KS, 1)>(vb);
;     ...
;     asm volatile("s_waitcnt lgkmcnt(6)" ::: "memory"); SBAR();
;     o[0] = __builtin_amdgcn_mfma_f32_32x32x16_bf16(pa, PK(l0, h0), o[0], 0, 0, 0);
;     asm volatile("s_waitcnt lgkmcnt(4)" ::: "memory"); SBAR();
;     o[1] = __builtin_amdgcn_mfma_f32_32x32x16_bf16(pa, PK(l1, h1), o[1], 0, 0, 0);
;     asm volatile("s_waitcnt lgkmcnt(2)" ::: "memory"); SBAR();
;     o[2] = __builtin_amdgcn_mfma_f32_32x32x16_bf16(pa, PK(l2, h2), o[2], 0, 0, 0);
;     asm volatile("s_waitcnt lgkmcnt(0)" ::: "memory"); SBAR();
;     o[3] = __builtin_amdgcn_mfma_f32_32x32x16_bf16(pa, PK(l3, h3), o[3], 0, 0, 0);
;     ...
; }
; __device__ __forceinline__ void pv_d0(f32x16* o, int vb, bf16x8 pa0, bf16x8 pa1, bf16x8 pa2, bf16x8 pa3) {
;     __builtin_amdgcn_s_setprio(1);
;     pv_ks<0>(o, vb, pa0); pv_ks<1>(o, vb, pa1); pv_ks<2>(o, vb, pa2); pv_ks<3>(o, vb, pa3);
;     __builtin_amdgcn_s_setprio(0);
; }
; __device__ __forceinline__ void exp_half(f32x16& p) {
; #pragma unroll
;     for (int r = 0; r < 16; ++r) p[r] = __builtin_amdgcn_exp2f(p[r]);
; }
; __device__ __forceinline__ void pack_p(const f32x16& p0, const f32x16& p1, float& l_reg, bf16x8& pa0, bf16x8& pa1, bf16x8& pa2, bf16x8& pa3) {
;     float ps = 0;
; #pragma unroll
;     for (int r = 0; r < 16; ++r) ps += p0[r];
; #pragma unroll
;     for (int r = 0; r < 16; ++r) ps += p1[r];
;     l_reg += ps;
;     ...
;     PK4(p0, 0, pa0); PK4(p0, 8, pa1); PK4(p1, 0, pa2); PK4(p1, 8, pa3);
;     ...
; }
; template <int ND0> __device__ __forceinline__ void qkt(f32x16& p0, f32x16& p1, const char* Ks, const bf16x8* qr, int r32, int hi, int colB0) {
; #pragma unroll
;     for (int d0 = 0; d0 < ND0; ++d0) { const int cb = colB0 + (d0 * 16 + hi * 8) * 2;
;         const bf16x8 b0 = *reinterpret_cast<const bf16x8*>(Ks + KSWZ(r32, cb));
;         const bf16x8 b1 = *reinterpret_cast<const bf16x8*>(Ks + KSWZ(32 + r32, cb));
;         p0 = __builtin_amdgcn_mfma_f32_32x32x16_bf16(b0, qr[d0], p0, 0, 0, 0);
.Lsym_biasdone_ys0:
	s_add_i32 s55, s55, 64
	v_add_f32_e32 v183, 0xc2800000, v183
	ds_read_b64_tr_b16 v[144:145], v252 offset:0
	ds_read_b64_tr_b16 v[146:147], v252 offset:2048
	ds_read_b64_tr_b16 v[148:149], v252 offset:512
	ds_read_b64_tr_b16 v[150:151], v252 offset:2560
	ds_read_b64_tr_b16 v[152:153], v252 offset:1024
	ds_read_b64_tr_b16 v[154:155], v252 offset:3072
	ds_read_b64_tr_b16 v[156:157], v252 offset:1536
	ds_read_b64_tr_b16 v[158:159], v252 offset:3584
	s_setprio 0
	s_waitcnt lgkmcnt(4)
	v_mfma_f32_32x32x16_bf16 v[48:63], v[128:131], v[144:147], v[48:63]
	ds_read_b64_tr_b16 v[144:145], v252 offset:4096
	ds_read_b64_tr_b16 v[146:147], v252 offset:6144
	v_exp_f32_e32 v88, v88
	v_exp_f32_e32 v89, v89
	v_mfma_f32_32x32x16_bf16 v[32:47], v[128:131], v[148:151], v[32:47]
	ds_read_b64_tr_b16 v[148:149], v252 offset:4608
	ds_read_b64_tr_b16 v[150:151], v252 offset:6656
	v_exp_f32_e32 v90, v90
	v_exp_f32_e32 v91, v91
	v_add_f32_e32 v182, v88, v182
	v_add_f32_e32 v182, v89, v182
	v_cvt_pk_bf16_f32 v132, v88, v89
	s_waitcnt lgkmcnt(4)
	v_mfma_f32_32x32x16_bf16 v[16:31], v[128:131], v[152:155], v[16:31]
	ds_read_b64_tr_b16 v[152:153], v252 offset:5120
	ds_read_b64_tr_b16 v[154:155], v252 offset:7168
	v_exp_f32_e32 v92, v92
	v_exp_f32_e32 v93, v93
	v_add_f32_e32 v182, v90, v182
	v_add_f32_e32 v182, v91, v182
	v_cvt_pk_bf16_f32 v133, v90, v91
	v_mfma_f32_32x32x16_bf16 v[0:15], v[128:131], v[156:159], v[0:15]
	ds_read_b64_tr_b16 v[156:157], v252 offset:5632
	ds_read_b64_tr_b16 v[158:159], v252 offset:7680
	v_exp_f32_e32 v94, v94
	v_exp_f32_e32 v95, v95
	v_add_f32_e32 v182, v92, v182
	v_add_f32_e32 v182, v93, v182
	v_cvt_pk_bf16_f32 v134, v92, v93
	v_cvt_pk_bf16_f32 v135, v94, v95
	v_add_f32_e32 v182, v94, v182
	v_add_f32_e32 v182, v95, v182
	v_mfma_f32_32x32x16_bf16 v[112:127], v[192:195], v[172:175], v[112:127]
	v_mfma_f32_32x32x16_bf16 v[96:111], v[196:199], v[172:175], v[96:111]
	v_mfma_f32_32x32x16_bf16 v[112:127], v[200:203], v[168:171], v[112:127]
	v_mfma_f32_32x32x16_bf16 v[96:111], v[204:207], v[168:171], v[96:111]
	s_setprio 1
	s_waitcnt lgkmcnt(4)
	v_mfma_f32_32x32x16_bf16 v[48:63], v[132:135], v[144:147], v[48:63]
	ds_read_b64_tr_b16 v[144:145], v252 offset:8192
	ds_read_b64_tr_b16 v[146:147], v252 offset:10240
	v_exp_f32_e32 v64, v64
	v_exp_f32_e32 v65, v65
	v_mfma_f32_32x32x16_bf16 v[32:47], v[132:135], v[148:151], v[32:47]
	ds_read_b64_tr_b16 v[148:149], v252 offset:8704
	ds_read_b64_tr_b16 v[150:151], v252 offset:10752
	v_exp_f32_e32 v66, v66
	v_exp_f32_e32 v67, v67
	v_add_f32_e32 v182, v64, v182
	v_add_f32_e32 v182, v65, v182
	v_cvt_pk_bf16_f32 v136, v64, v65
	s_waitcnt lgkmcnt(4)
	v_mfma_f32_32x32x16_bf16 v[16:31], v[132:135], v[152:155], v[16:31]
	ds_read_b64_tr_b16 v[152:153], v252 offset:9216
	ds_read_b64_tr_b16 v[154:155], v252 offset:11264
	v_exp_f32_e32 v68, v68
	v_exp_f32_e32 v69, v69
	v_add_f32_e32 v182, v66, v182
	v_add_f32_e32 v182, v67, v182
	v_cvt_pk_bf16_f32 v137, v66, v67
	v_mfma_f32_32x32x16_bf16 v[0:15], v[132:135], v[156:159], v[0:15]
	ds_read_b64_tr_b16 v[156:157], v252 offset:9728
	ds_read_b64_tr_b16 v[158:159], v252 offset:11776
	v_exp_f32_e32 v70, v70
	v_exp_f32_e32 v71, v71
	v_add_f32_e32 v182, v68, v182
	v_add_f32_e32 v182, v69, v182
	v_cvt_pk_bf16_f32 v138, v68, v69
	v_cvt_pk_bf16_f32 v139, v70, v71
	v_add_f32_e32 v182, v70, v182
	v_add_f32_e32 v182, v71, v182
	v_mfma_f32_32x32x16_bf16 v[112:127], v[208:211], v[164:167], v[112:127]
	v_mfma_f32_32x32x16_bf16 v[96:111], v[212:215], v[164:167], v[96:111]
	v_mfma_f32_32x32x16_bf16 v[112:127], v[216:219], v[160:163], v[112:127]
	v_mfma_f32_32x32x16_bf16 v[96:111], v[220:223], v[160:163], v[96:111]
	s_setprio 0
	s_waitcnt lgkmcnt(4)
	v_mfma_f32_32x32x16_bf16 v[48:63], v[136:139], v[144:147], v[48:63]
	ds_read_b64_tr_b16 v[144:145], v252 offset:12288
	ds_read_b64_tr_b16 v[146:147], v252 offset:14336
	v_exp_f32_e32 v72, v72
	v_exp_f32_e32 v73, v73
	v_mfma_f32_32x32x16_bf16 v[32:47], v[136:139], v[148:151], v[32:47]
	ds_read_b64_tr_b16 v[148:149], v252 offset:12800
	ds_read_b64_tr_b16 v[150:151], v252 offset:14848
	v_exp_f32_e32 v74, v74
	v_exp_f32_e32 v75, v75
	v_add_f32_e32 v182, v72, v182
	v_add_f32_e32 v182, v73, v182
	v_cvt_pk_bf16_f32 v140, v72, v73
	s_waitcnt lgkmcnt(4)
	v_mfma_f32_32x32x16_bf16 v[16:31], v[136:139], v[152:155], v[16:31]
	ds_read_b64_tr_b16 v[152:153], v252 offset:13312
	ds_read_b64_tr_b16 v[154:155], v252 offset:15360
	v_exp_f32_e32 v76, v76
	v_exp_f32_e32 v77, v77
	v_add_f32_e32 v182, v74, v182
	v_add_f32_e32 v182, v75, v182
	v_cvt_pk_bf16_f32 v141, v74, v75
	v_mfma_f32_32x32x16_bf16 v[0:15], v[136:139], v[156:159], v[0:15]
	ds_read_b64_tr_b16 v[156:157], v252 offset:13824
	ds_read_b64_tr_b16 v[158:159], v252 offset:15872
	v_exp_f32_e32 v78, v78
	v_exp_f32_e32 v79, v79
	v_add_f32_e32 v182, v76, v182
	v_add_f32_e32 v182, v77, v182
	v_cvt_pk_bf16_f32 v142, v76, v77
	v_cvt_pk_bf16_f32 v143, v78, v79
	v_add_f32_e32 v182, v78, v182
	v_add_f32_e32 v182, v79, v182
	s_setprio 1
	s_waitcnt lgkmcnt(4)
	v_mfma_f32_32x32x16_bf16 v[48:63], v[140:143], v[144:147], v[48:63]
	v_exp_f32_e32 v112, v112
	v_exp_f32_e32 v113, v113
	v_mfma_f32_32x32x16_bf16 v[32:47], v[140:143], v[148:151], v[32:47]
	v_exp_f32_e32 v114, v114
	v_exp_f32_e32 v115, v115
	v_add_f32_e32 v182, v112, v182
	v_add_f32_e32 v182, v113, v182
	v_cvt_pk_bf16_f32 v128, v112, v113
	s_waitcnt lgkmcnt(0)
	v_mfma_f32_32x32x16_bf16 v[16:31], v[140:143], v[152:155], v[16:31]
	v_exp_f32_e32 v116, v116
	v_exp_f32_e32 v117, v117
	v_add_f32_e32 v182, v114, v182
	v_add_f32_e32 v182, v115, v182
	v_cvt_pk_bf16_f32 v129, v114, v115
	v_mfma_f32_32x32x16_bf16 v[0:15], v[140:143], v[156:159], v[0:15]
	v_exp_f32_e32 v118, v118
	v_exp_f32_e32 v119, v119
	v_add_f32_e32 v182, v116, v182
	v_add_f32_e32 v182, v117, v182
	v_cvt_pk_bf16_f32 v130, v116, v117
	v_cvt_pk_bf16_f32 v131, v118, v119
	v_add_f32_e32 v182, v118, v182
	v_add_f32_e32 v182, v119, v182
	s_add_i32 s54, s54, 1
	s_cmp_ge_i32 s54, s62
	s_cbranch_scc1 .Lsym_last1_y
	s_waitcnt vmcnt(0)
	s_barrier
	ds_read_b128 v[192:195], v178 offset:32768
	ds_read_b128 v[196:199], v178 offset:40960
	ds_read_b128 v[200:203], v179 offset:32768
	ds_read_b128 v[204:207], v179 offset:40960
	ds_read_b128 v[208:211], v180 offset:32768
	ds_read_b128 v[212:215], v180 offset:40960
	ds_read_b128 v[216:219], v181 offset:32768
	ds_read_b128 v[220:223], v181 offset:40960
	s_add_i32 s53, s54, 2
	s_cmp_le_i32 s53, s62
	s_cbranch_scc0 .Lsym_nostage_ys1
	s_add_i32 m0, s25, 0xc000
	s_add_u32 s60, s56, 0x70000
	s_addc_u32 s61, s57, 0
	global_load_lds_dwordx4 v176, s[56:57]
	s_add_i32 m0, s24, 0xc000
	s_nop 0
	global_load_lds_dwordx4 v188, s[56:57]
	s_add_i32 m0, s25, 0xe000
	s_add_u32 s56, s56, 0xe0000
	s_addc_u32 s57, s57, 0
	global_load_lds_dwordx4 v176, s[60:61]
	s_add_i32 m0, s24, 0xe000
	s_nop 0
	global_load_lds_dwordx4 v188, s[60:61]

; template <int KS> __device__ __forceinline__ void pv_ks(f32x16* o, int vb, bf16x8 pa) {
;     const s16x4 l0 = tr_read<v_rd_off(0, KS, 0)>(vb), h0 = tr_read<v_rd_off(0, KS, 1)>(vb), l1 = tr_read<v_rd_off(1, KS, 0)>(vb), h1 = tr_read<v_rd_off(1, KS, 1)>(vb);
;     const s16x4 l2 = tr_read<v_rd_off(2, KS, 0)>(vb), h2 = tr_read<v_rd_off(2, KS, 1)>(vb), l3 = tr_read<v_rd_off(3, KS, 0)>(vb), h3 = tr_read<v_rd_off(3, KS, 1)>(vb);
;     ...
;     asm volatile("s_waitcnt lgkmcnt(6)" ::: "memory"); SBAR();
;     o[0] = __builtin_amdgcn_mfma_f32_32x32x16_bf16(pa, PK(l0, h0), o[0], 0, 0, 0);
;     asm volatile("s_waitcnt lgkmcnt(4)" ::: "memory"); SBAR();
;     o[1] = __builtin_amdgcn_mfma_f32_32x32x16_bf16(pa, PK(l1, h1), o[1], 0, 0, 0);
;     asm volatile("s_waitcnt lgkmcnt(2)" ::: "memory"); SBAR();
;     o[2] = __builtin_amdgcn_mfma_f32_32x32x16_bf16(pa, PK(l2, h2), o[2], 0, 0, 0);
;     asm volatile("s_waitcnt lgkmcnt(0)" ::: "memory"); SBAR();
;     o[3] = __builtin_amdgcn_mfma_f32_32x32x16_bf16(pa, PK(l3, h3), o[3], 0, 0, 0);
;     ...
; }
; __device__ __forceinline__ void pv_d0(f32x16* o, int vb, bf16x8 pa0, bf16x8 pa1, bf16x8 pa2, bf16x8 pa3) {
;     __builtin_amdgcn_s_setprio(1);
;     pv_ks<0>(o, vb, pa0); pv_ks<1>(o, vb, pa1); pv_ks<2>(o, vb, pa2); pv_ks<3>(o, vb, pa3);
;     __builtin_amdgcn_s_setprio(0);
; }
; __device__ __forceinline__ void exp_half(f32x16& p) {
; #pragma unroll
;     for (int r = 0; r < 16; ++r) p[r] = __builtin_amdgcn_exp2f(p[r]);
; }
; __device__ __forceinline__ void pack_p(const f32x16& p0, const f32x16& p1, float& l_reg, bf16x8& pa0, bf16x8& pa1, bf16x8& pa2, bf16x8& pa3) {
;     float ps = 0;
; #pragma unroll
;     for (int r = 0; r < 16; ++r) ps += p0[r];
; #pragma unroll
;     for (int r = 0; r < 16; ++r) ps += p1[r];
;     l_reg += ps;
;     ...
;     PK4(p0, 0, pa0); PK4(p0, 8, pa1); PK4(p1, 0, pa2); PK4(p1, 8, pa3);
;     ...
; }
; template <int ND0> __device__ __forceinline__ void qkt(f32x16& p0, f32x16& p1, const char* Ks, const bf16x8* qr, int r32, int hi, int colB0) {
; #pragma unroll
;     for (int d0 = 0; d0 < ND0; ++d0) { const int cb = colB0 + (d0 * 16 + hi * 8) * 2;
;         const bf16x8 b0 = *reinterpret_cast<const bf16x8*>(Ks + KSWZ(r32, cb));
;         const bf16x8 b1 = *reinterpret_cast<const bf16x8*>(Ks + KSWZ(32 + r32, cb));
;         p0 = __builtin_amdgcn_mfma_f32_32x32x16_bf16(b0, qr[d0], p0, 0, 0, 0);
.Lsym_biasdone_ys1:
	s_add_i32 s55, s55, 64
	v_add_f32_e32 v183, 0xc2800000, v183
	ds_read_b64_tr_b16 v[144:145], v252 offset:16384
	ds_read_b64_tr_b16 v[146:147], v252 offset:18432
	ds_read_b64_tr_b16 v[148:149], v252 offset:16896
	ds_read_b64_tr_b16 v[150:151], v252 offset:18944
	ds_read_b64_tr_b16 v[152:153], v252 offset:17408
	ds_read_b64_tr_b16 v[154:155], v252 offset:19456
	ds_read_b64_tr_b16 v[156:157], v252 offset:17920
	ds_read_b64_tr_b16 v[158:159], v252 offset:19968
	s_setprio 0
	s_waitcnt lgkmcnt(4)
	v_mfma_f32_32x32x16_bf16 v[48:63], v[128:131], v[144:147], v[48:63]
	ds_read_b64_tr_b16 v[144:145], v252 offset:20480
	ds_read_b64_tr_b16 v[146:147], v252 offset:22528
	v_exp_f32_e32 v120, v120
	v_exp_f32_e32 v121, v121
	v_mfma_f32_32x32x16_bf16 v[32:47], v[128:131], v[148:151], v[32:47]
	ds_read_b64_tr_b16 v[148:149], v252 offset:20992
	ds_read_b64_tr_b16 v[150:151], v252 offset:23040
	v_exp_f32_e32 v122, v122
	v_exp_f32_e32 v123, v123
	v_add_f32_e32 v182, v120, v182
	v_add_f32_e32 v182, v121, v182
	v_cvt_pk_bf16_f32 v132, v120, v121
	s_waitcnt lgkmcnt(4)
	v_mfma_f32_32x32x16_bf16 v[16:31], v[128:131], v[152:155], v[16:31]
	ds_read_b64_tr_b16 v[152:153], v252 offset:21504
	ds_read_b64_tr_b16 v[154:155], v252 offset:23552
	v_exp_f32_e32 v124, v124
	v_exp_f32_e32 v125, v125
	v_add_f32_e32 v182, v122, v182
	v_add_f32_e32 v182, v123, v182
	v_cvt_pk_bf16_f32 v133, v122, v123
	v_mfma_f32_32x32x16_bf16 v[0:15], v[128:131], v[156:159], v[0:15]
	ds_read_b64_tr_b16 v[156:157], v252 offset:22016
	ds_read_b64_tr_b16 v[158:159], v252 offset:24064
	v_exp_f32_e32 v126, v126
	v_exp_f32_e32 v127, v127
	v_add_f32_e32 v182, v124, v182
	v_add_f32_e32 v182, v125, v182
	v_cvt_pk_bf16_f32 v134, v124, v125
	v_cvt_pk_bf16_f32 v135, v126, v127
	v_add_f32_e32 v182, v126, v182
	v_add_f32_e32 v182, v127, v182
	v_mfma_f32_32x32x16_bf16 v[80:95], v[192:195], v[172:175], v[80:95]
	v_mfma_f32_32x32x16_bf16 v[64:79], v[196:199], v[172:175], v[64:79]
	v_mfma_f32_32x32x16_bf16 v[80:95], v[200:203], v[168:171], v[80:95]
	v_mfma_f32_32x32x16_bf16 v[64:79], v[204:207], v[168:171], v[64:79]
	s_setprio 1
	s_waitcnt lgkmcnt(4)
	v_mfma_f32_32x32x16_bf16 v[48:63], v[132:135], v[144:147], v[48:63]
	ds_read_b64_tr_b16 v[144:145], v252 offset:24576
	ds_read_b64_tr_b16 v[146:147], v252 offset:26624
	v_exp_f32_e32 v96, v96
	v_exp_f32_e32 v97, v97
	v_mfma_f32_32x32x16_bf16 v[32:47], v[132:135], v[148:151], v[32:47]
	ds_read_b64_tr_b16 v[148:149], v252 offset:25088
	ds_read_b64_tr_b16 v[150:151], v252 offset:27136
	v_exp_f32_e32 v98, v98
	v_exp_f32_e32 v99, v99
	v_add_f32_e32 v182, v96, v182
	v_add_f32_e32 v182, v97, v182
	v_cvt_pk_bf16_f32 v136, v96, v97
	s_waitcnt lgkmcnt(4)
	v_mfma_f32_32x32x16_bf16 v[16:31], v[132:135], v[152:155], v[16:31]
	ds_read_b64_tr_b16 v[152:153], v252 offset:25600
	ds_read_b64_tr_b16 v[154:155], v252 offset:27648
	v_exp_f32_e32 v100, v100
	v_exp_f32_e32 v101, v101
	v_add_f32_e32 v182, v98, v182
	v_add_f32_e32 v182, v99, v182
	v_cvt_pk_bf16_f32 v137, v98, v99
	v_mfma_f32_32x32x16_bf16 v[0:15], v[132:135], v[156:159], v[0:15]
	ds_read_b64_tr_b16 v[156:157], v252 offset:26112
	ds_read_b64_tr_b16 v[158:159], v252 offset:28160
	v_exp_f32_e32 v102, v102
	v_exp_f32_e32 v103, v103
	v_add_f32_e32 v182, v100, v182
	v_add_f32_e32 v182, v101, v182
	v_cvt_pk_bf16_f32 v138, v100, v101
	v_cvt_pk_bf16_f32 v139, v102, v103
	v_add_f32_e32 v182, v102, v182
	v_add_f32_e32 v182, v103, v182
	v_mfma_f32_32x32x16_bf16 v[80:95], v[208:211], v[164:167], v[80:95]
	v_mfma_f32_32x32x16_bf16 v[64:79], v[212:215], v[164:167], v[64:79]
	v_mfma_f32_32x32x16_bf16 v[80:95], v[216:219], v[160:163], v[80:95]
	v_mfma_f32_32x32x16_bf16 v[64:79], v[220:223], v[160:163], v[64:79]
	s_setprio 0
	s_waitcnt lgkmcnt(4)
	v_mfma_f32_32x32x16_bf16 v[48:63], v[136:139], v[144:147], v[48:63]
	ds_read_b64_tr_b16 v[144:145], v252 offset:28672
	ds_read_b64_tr_b16 v[146:147], v252 offset:30720
	v_exp_f32_e32 v104, v104
	v_exp_f32_e32 v105, v105
	v_mfma_f32_32x32x16_bf16 v[32:47], v[136:139], v[148:151], v[32:47]
	ds_read_b64_tr_b16 v[148:149], v252 offset:29184
	ds_read_b64_tr_b16 v[150:151], v252 offset:31232
	v_exp_f32_e32 v106, v106
	v_exp_f32_e32 v107, v107
	v_add_f32_e32 v182, v104, v182
	v_add_f32_e32 v182, v105, v182
	v_cvt_pk_bf16_f32 v140, v104, v105
	s_waitcnt lgkmcnt(4)
	v_mfma_f32_32x32x16_bf16 v[16:31], v[136:139], v[152:155], v[16:31]
	ds_read_b64_tr_b16 v[152:153], v252 offset:29696
	ds_read_b64_tr_b16 v[154:155], v252 offset:31744
	v_exp_f32_e32 v108, v108
	v_exp_f32_e32 v109, v109
	v_add_f32_e32 v182, v106, v182
	v_add_f32_e32 v182, v107, v182
	v_cvt_pk_bf16_f32 v141, v106, v107
	v_mfma_f32_32x32x16_bf16 v[0:15], v[136:139], v[156:159], v[0:15]
	ds_read_b64_tr_b16 v[156:157], v252 offset:30208
	ds_read_b64_tr_b16 v[158:159], v252 offset:32256
	v_exp_f32_e32 v110, v110
	v_exp_f32_e32 v111, v111
	v_add_f32_e32 v182, v108, v182
	v_add_f32_e32 v182, v109, v182
	v_cvt_pk_bf16_f32 v142, v108, v109
	v_cvt_pk_bf16_f32 v143, v110, v111
	v_add_f32_e32 v182, v110, v182
	v_add_f32_e32 v182, v111, v182
	s_setprio 1
	s_waitcnt lgkmcnt(4)
	v_mfma_f32_32x32x16_bf16 v[48:63], v[140:143], v[144:147], v[48:63]
	v_exp_f32_e32 v80, v80
	v_exp_f32_e32 v81, v81
	v_mfma_f32_32x32x16_bf16 v[32:47], v[140:143], v[148:151], v[32:47]
	v_exp_f32_e32 v82, v82
	v_exp_f32_e32 v83, v83
	v_add_f32_e32 v182, v80, v182
	v_add_f32_e32 v182, v81, v182
	v_cvt_pk_bf16_f32 v128, v80, v81
	s_waitcnt lgkmcnt(0)
	v_mfma_f32_32x32x16_bf16 v[16:31], v[140:143], v[152:155], v[16:31]
	v_exp_f32_e32 v84, v84
	v_exp_f32_e32 v85, v85
	v_add_f32_e32 v182, v82, v182
	v_add_f32_e32 v182, v83, v182
	v_cvt_pk_bf16_f32 v129, v82, v83
	v_mfma_f32_32x32x16_bf16 v[0:15], v[140:143], v[156:159], v[0:15]
	v_exp_f32_e32 v86, v86
	v_exp_f32_e32 v87, v87
	v_add_f32_e32 v182, v84, v182
	v_add_f32_e32 v182, v85, v182
	v_cvt_pk_bf16_f32 v130, v84, v85
	v_cvt_pk_bf16_f32 v131, v86, v87
	v_add_f32_e32 v182, v86, v182
	v_add_f32_e32 v182, v87, v182
	s_add_i32 s54, s54, 1
	s_waitcnt vmcnt(0)
	s_barrier
	ds_read_b128 v[192:195], v178 offset:49152
	ds_read_b128 v[196:199], v178 offset:57344
	ds_read_b128 v[200:203], v179 offset:49152
	ds_read_b128 v[204:207], v179 offset:57344
	ds_read_b128 v[208:211], v180 offset:49152
	ds_read_b128 v[212:215], v180 offset:57344
	ds_read_b128 v[216:219], v181 offset:49152
	ds_read_b128 v[220:223], v181 offset:57344
	s_add_i32 s53, s54, 2
	s_cmp_le_i32 s53, s62
	s_cbranch_scc0 .Lsym_nostage_ys2
	s_add_i32 m0, s25, 0x0
	s_add_u32 s60, s56, 0x70000
	s_addc_u32 s61, s57, 0
	global_load_lds_dwordx4 v176, s[56:57]
	s_add_i32 m0, s24, 0x0
	s_nop 0
	global_load_lds_dwordx4 v188, s[56:57]
	s_add_i32 m0, s25, 0x2000
	s_add_u32 s56, s56, 0xe0000
	s_addc_u32 s57, s57, 0
	global_load_lds_dwordx4 v176, s[60:61]
	s_add_i32 m0, s24, 0x2000
	s_nop 0
	global_load_lds_dwordx4 v188, s[60:61]

; template <int KS> __device__ __forceinline__ void pv_ks(f32x16* o, int vb, bf16x8 pa) {
;     const s16x4 l0 = tr_read<v_rd_off(0, KS, 0)>(vb), h0 = tr_read<v_rd_off(0, KS, 1)>(vb), l1 = tr_read<v_rd_off(1, KS, 0)>(vb), h1 = tr_read<v_rd_off(1, KS, 1)>(vb);
;     const s16x4 l2 = tr_read<v_rd_off(2, KS, 0)>(vb), h2 = tr_read<v_rd_off(2, KS, 1)>(vb), l3 = tr_read<v_rd_off(3, KS, 0)>(vb), h3 = tr_read<v_rd_off(3, KS, 1)>(vb);
;     ...
;     asm volatile("s_waitcnt lgkmcnt(6)" ::: "memory"); SBAR();
;     o[0] = __builtin_amdgcn_mfma_f32_32x32x16_bf16(pa, PK(l0, h0), o[0], 0, 0, 0);
;     asm volatile("s_waitcnt lgkmcnt(4)" ::: "memory"); SBAR();
;     o[1] = __builtin_amdgcn_mfma_f32_32x32x16_bf16(pa, PK(l1, h1), o[1], 0, 0, 0);
;     asm volatile("s_waitcnt lgkmcnt(2)" ::: "memory"); SBAR();
;     o[2] = __builtin_amdgcn_mfma_f32_32x32x16_bf16(pa, PK(l2, h2), o[2], 0, 0, 0);
;     asm volatile("s_waitcnt lgkmcnt(0)" ::: "memory"); SBAR();
;     o[3] = __builtin_amdgcn_mfma_f32_32x32x16_bf16(pa, PK(l3, h3), o[3], 0, 0, 0);
;     ...
; }
; __device__ __forceinline__ void pv_d0(f32x16* o, int vb, bf16x8 pa0, bf16x8 pa1, bf16x8 pa2, bf16x8 pa3) {
;     __builtin_amdgcn_s_setprio(1);
;     pv_ks<0>(o, vb, pa0); pv_ks<1>(o, vb, pa1); pv_ks<2>(o, vb, pa2); pv_ks<3>(o, vb, pa3);
;     __builtin_amdgcn_s_setprio(0);
; }
; __device__ __forceinline__ void exp_half(f32x16& p) {
; #pragma unroll
;     for (int r = 0; r < 16; ++r) p[r] = __builtin_amdgcn_exp2f(p[r]);
; }
; __device__ __forceinline__ void pack_p(const f32x16& p0, const f32x16& p1, float& l_reg, bf16x8& pa0, bf16x8& pa1, bf16x8& pa2, bf16x8& pa3) {
;     float ps = 0;
; #pragma unroll
;     for (int r = 0; r < 16; ++r) ps += p0[r];
; #pragma unroll
;     for (int r = 0; r < 16; ++r) ps += p1[r];
;     l_reg += ps;
;     ...
;     PK4(p0, 0, pa0); PK4(p0, 8, pa1); PK4(p1, 0, pa2); PK4(p1, 8, pa3);
;     ...
; }
; template <int ND0> __device__ __forceinline__ void qkt(f32x16& p0, f32x16& p1, const char* Ks, const bf16x8* qr, int r32, int hi, int colB0) {
; #pragma unroll
;     for (int d0 = 0; d0 < ND0; ++d0) { const int cb = colB0 + (d0 * 16 + hi * 8) * 2;
;         const bf16x8 b0 = *reinterpret_cast<const bf16x8*>(Ks + KSWZ(r32, cb));
;         const bf16x8 b1 = *reinterpret_cast<const bf16x8*>(Ks + KSWZ(32 + r32, cb));
;         p0 = __builtin_amdgcn_mfma_f32_32x32x16_bf16(b0, qr[d0], p0, 0, 0, 0);
.Lsym_biasdone_ys2:
	s_add_i32 s55, s55, 64
	v_add_f32_e32 v183, 0xc2800000, v183
	ds_read_b64_tr_b16 v[144:145], v252 offset:32768
	ds_read_b64_tr_b16 v[146:147], v252 offset:34816
	ds_read_b64_tr_b16 v[148:149], v252 offset:33280
	ds_read_b64_tr_b16 v[150:151], v252 offset:35328
	ds_read_b64_tr_b16 v[152:153], v252 offset:33792
	ds_read_b64_tr_b16 v[154:155], v252 offset:35840
	ds_read_b64_tr_b16 v[156:157], v252 offset:34304
	ds_read_b64_tr_b16 v[158:159], v252 offset:36352
	s_setprio 0
	s_waitcnt lgkmcnt(4)
	v_mfma_f32_32x32x16_bf16 v[48:63], v[128:131], v[144:147], v[48:63]
	ds_read_b64_tr_b16 v[144:145], v252 offset:36864
	ds_read_b64_tr_b16 v[146:147], v252 offset:38912
	v_exp_f32_e32 v88, v88
	v_exp_f32_e32 v89, v89
	v_mfma_f32_32x32x16_bf16 v[32:47], v[128:131], v[148:151], v[32:47]
	ds_read_b64_tr_b16 v[148:149], v252 offset:37376
	ds_read_b64_tr_b16 v[150:151], v252 offset:39424
	v_exp_f32_e32 v90, v90
	v_exp_f32_e32 v91, v91
	v_add_f32_e32 v182, v88, v182
	v_add_f32_e32 v182, v89, v182
	v_cvt_pk_bf16_f32 v132, v88, v89
	s_waitcnt lgkmcnt(4)
	v_mfma_f32_32x32x16_bf16 v[16:31], v[128:131], v[152:155], v[16:31]
	ds_read_b64_tr_b16 v[152:153], v252 offset:37888
	ds_read_b64_tr_b16 v[154:155], v252 offset:39936
	v_exp_f32_e32 v92, v92
	v_exp_f32_e32 v93, v93
	v_add_f32_e32 v182, v90, v182
	v_add_f32_e32 v182, v91, v182
	v_cvt_pk_bf16_f32 v133, v90, v91
	v_mfma_f32_32x32x16_bf16 v[0:15], v[128:131], v[156:159], v[0:15]
	ds_read_b64_tr_b16 v[156:157], v252 offset:38400
	ds_read_b64_tr_b16 v[158:159], v252 offset:40448
	v_exp_f32_e32 v94, v94
	v_exp_f32_e32 v95, v95
	v_add_f32_e32 v182, v92, v182
	v_add_f32_e32 v182, v93, v182
	v_cvt_pk_bf16_f32 v134, v92, v93
	v_cvt_pk_bf16_f32 v135, v94, v95
	v_add_f32_e32 v182, v94, v182
	v_add_f32_e32 v182, v95, v182
	v_mfma_f32_32x32x16_bf16 v[112:127], v[192:195], v[172:175], v[112:127]
	v_mfma_f32_32x32x16_bf16 v[96:111], v[196:199], v[172:175], v[96:111]
	v_mfma_f32_32x32x16_bf16 v[112:127], v[200:203], v[168:171], v[112:127]
	v_mfma_f32_32x32x16_bf16 v[96:111], v[204:207], v[168:171], v[96:111]
	s_setprio 1
	s_waitcnt lgkmcnt(4)
	v_mfma_f32_32x32x16_bf16 v[48:63], v[132:135], v[144:147], v[48:63]
	ds_read_b64_tr_b16 v[144:145], v252 offset:40960
	ds_read_b64_tr_b16 v[146:147], v252 offset:43008
	v_exp_f32_e32 v64, v64
	v_exp_f32_e32 v65, v65
	v_mfma_f32_32x32x16_bf16 v[32:47], v[132:135], v[148:151], v[32:47]
	ds_read_b64_tr_b16 v[148:149], v252 offset:41472
	ds_read_b64_tr_b16 v[150:151], v252 offset:43520
	v_exp_f32_e32 v66, v66
	v_exp_f32_e32 v67, v67
	v_add_f32_e32 v182, v64, v182
	v_add_f32_e32 v182, v65, v182
	v_cvt_pk_bf16_f32 v136, v64, v65
	s_waitcnt lgkmcnt(4)
	v_mfma_f32_32x32x16_bf16 v[16:31], v[132:135], v[152:155], v[16:31]
	ds_read_b64_tr_b16 v[152:153], v252 offset:41984
	ds_read_b64_tr_b16 v[154:155], v252 offset:44032
	v_exp_f32_e32 v68, v68
	v_exp_f32_e32 v69, v69
	v_add_f32_e32 v182, v66, v182
	v_add_f32_e32 v182, v67, v182
	v_cvt_pk_bf16_f32 v137, v66, v67
	v_mfma_f32_32x32x16_bf16 v[0:15], v[132:135], v[156:159], v[0:15]
	ds_read_b64_tr_b16 v[156:157], v252 offset:42496
	ds_read_b64_tr_b16 v[158:159], v252 offset:44544
	v_exp_f32_e32 v70, v70
	v_exp_f32_e32 v71, v71
	v_add_f32_e32 v182, v68, v182
	v_add_f32_e32 v182, v69, v182
	v_cvt_pk_bf16_f32 v138, v68, v69
	v_cvt_pk_bf16_f32 v139, v70, v71
	v_add_f32_e32 v182, v70, v182
	v_add_f32_e32 v182, v71, v182
	v_mfma_f32_32x32x16_bf16 v[112:127], v[208:211], v[164:167], v[112:127]
	v_mfma_f32_32x32x16_bf16 v[96:111], v[212:215], v[164:167], v[96:111]
	v_mfma_f32_32x32x16_bf16 v[112:127], v[216:219], v[160:163], v[112:127]
	v_mfma_f32_32x32x16_bf16 v[96:111], v[220:223], v[160:163], v[96:111]
	s_setprio 0
	s_waitcnt lgkmcnt(4)
	v_mfma_f32_32x32x16_bf16 v[48:63], v[136:139], v[144:147], v[48:63]
	ds_read_b64_tr_b16 v[144:145], v252 offset:45056
	ds_read_b64_tr_b16 v[146:147], v252 offset:47104
	v_exp_f32_e32 v72, v72
	v_exp_f32_e32 v73, v73
	v_mfma_f32_32x32x16_bf16 v[32:47], v[136:139], v[148:151], v[32:47]
	ds_read_b64_tr_b16 v[148:149], v252 offset:45568
	ds_read_b64_tr_b16 v[150:151], v252 offset:47616
	v_exp_f32_e32 v74, v74
	v_exp_f32_e32 v75, v75
	v_add_f32_e32 v182, v72, v182
	v_add_f32_e32 v182, v73, v182
	v_cvt_pk_bf16_f32 v140, v72, v73
	s_waitcnt lgkmcnt(4)
	v_mfma_f32_32x32x16_bf16 v[16:31], v[136:139], v[152:155], v[16:31]
	ds_read_b64_tr_b16 v[152:153], v252 offset:46080
	ds_read_b64_tr_b16 v[154:155], v252 offset:48128
	v_exp_f32_e32 v76, v76
	v_exp_f32_e32 v77, v77
	v_add_f32_e32 v182, v74, v182
	v_add_f32_e32 v182, v75, v182
	v_cvt_pk_bf16_f32 v141, v74, v75
	v_mfma_f32_32x32x16_bf16 v[0:15], v[136:139], v[156:159], v[0:15]
	ds_read_b64_tr_b16 v[156:157], v252 offset:46592
	ds_read_b64_tr_b16 v[158:159], v252 offset:48640
	v_exp_f32_e32 v78, v78
	v_exp_f32_e32 v79, v79
	v_add_f32_e32 v182, v76, v182
	v_add_f32_e32 v182, v77, v182
	v_cvt_pk_bf16_f32 v142, v76, v77
	v_cvt_pk_bf16_f32 v143, v78, v79
	v_add_f32_e32 v182, v78, v182
	v_add_f32_e32 v182, v79, v182
	s_setprio 1
	s_waitcnt lgkmcnt(4)
	v_mfma_f32_32x32x16_bf16 v[48:63], v[140:143], v[144:147], v[48:63]
	v_exp_f32_e32 v112, v112
	v_exp_f32_e32 v113, v113
	v_mfma_f32_32x32x16_bf16 v[32:47], v[140:143], v[148:151], v[32:47]
	v_exp_f32_e32 v114, v114
	v_exp_f32_e32 v115, v115
	v_add_f32_e32 v182, v112, v182
	v_add_f32_e32 v182, v113, v182
	v_cvt_pk_bf16_f32 v128, v112, v113
	s_waitcnt lgkmcnt(0)
	v_mfma_f32_32x32x16_bf16 v[16:31], v[140:143], v[152:155], v[16:31]
	v_exp_f32_e32 v116, v116
	v_exp_f32_e32 v117, v117
	v_add_f32_e32 v182, v114, v182
	v_add_f32_e32 v182, v115, v182
	v_cvt_pk_bf16_f32 v129, v114, v115
	v_mfma_f32_32x32x16_bf16 v[0:15], v[140:143], v[156:159], v[0:15]
	v_exp_f32_e32 v118, v118
	v_exp_f32_e32 v119, v119
	v_add_f32_e32 v182, v116, v182
	v_add_f32_e32 v182, v117, v182
	v_cvt_pk_bf16_f32 v130, v116, v117
	v_cvt_pk_bf16_f32 v131, v118, v119
	v_add_f32_e32 v182, v118, v182
	v_add_f32_e32 v182, v119, v182
	s_add_i32 s54, s54, 1
	s_cmp_ge_i32 s54, s62
	s_cbranch_scc1 .Lsym_last3_y
	s_waitcnt vmcnt(0)
	s_barrier
	ds_read_b128 v[192:195], v178 offset:0
	ds_read_b128 v[196:199], v178 offset:8192
	ds_read_b128 v[200:203], v179 offset:0
	ds_read_b128 v[204:207], v179 offset:8192
	ds_read_b128 v[208:211], v180 offset:0
	ds_read_b128 v[212:215], v180 offset:8192
	ds_read_b128 v[216:219], v181 offset:0
	ds_read_b128 v[220:223], v181 offset:8192
	s_add_i32 s53, s54, 2
	s_cmp_le_i32 s53, s62
	s_cbranch_scc0 .Lsym_nostage_ys3
	s_add_i32 m0, s25, 0x4000
	s_add_u32 s60, s56, 0x70000
	s_addc_u32 s61, s57, 0
	global_load_lds_dwordx4 v176, s[56:57]
	s_add_i32 m0, s24, 0x4000
	s_nop 0
	global_load_lds_dwordx4 v188, s[56:57]
	s_add_i32 m0, s25, 0x6000
	s_add_u32 s56, s56, 0xe0000
	s_addc_u32 s57, s57, 0
	global_load_lds_dwordx4 v176, s[60:61]
	s_add_i32 m0, s24, 0x6000
	s_nop 0
	global_load_lds_dwordx4 v188, s[60:61]

; template <int KS> __device__ __forceinline__ void pv_ks(f32x16* o, int vb, bf16x8 pa) {
;     const s16x4 l0 = tr_read<v_rd_off(0, KS, 0)>(vb), h0 = tr_read<v_rd_off(0, KS, 1)>(vb), l1 = tr_read<v_rd_off(1, KS, 0)>(vb), h1 = tr_read<v_rd_off(1, KS, 1)>(vb);
;     const s16x4 l2 = tr_read<v_rd_off(2, KS, 0)>(vb), h2 = tr_read<v_rd_off(2, KS, 1)>(vb), l3 = tr_read<v_rd_off(3, KS, 0)>(vb), h3 = tr_read<v_rd_off(3, KS, 1)>(vb);
;     ...
;     asm volatile("s_waitcnt lgkmcnt(6)" ::: "memory"); SBAR();
;     o[0] = __builtin_amdgcn_mfma_f32_32x32x16_bf16(pa, PK(l0, h0), o[0], 0, 0, 0);
;     asm volatile("s_waitcnt lgkmcnt(4)" ::: "memory"); SBAR();
;     o[1] = __builtin_amdgcn_mfma_f32_32x32x16_bf16(pa, PK(l1, h1), o[1], 0, 0, 0);
;     asm volatile("s_waitcnt lgkmcnt(2)" ::: "memory"); SBAR();
;     o[2] = __builtin_amdgcn_mfma_f32_32x32x16_bf16(pa, PK(l2, h2), o[2], 0, 0, 0);
;     asm volatile("s_waitcnt lgkmcnt(0)" ::: "memory"); SBAR();
;     o[3] = __builtin_amdgcn_mfma_f32_32x32x16_bf16(pa, PK(l3, h3), o[3], 0, 0, 0);
;     ...
; }
; __device__ __forceinline__ void pv_d0(f32x16* o, int vb, bf16x8 pa0, bf16x8 pa1, bf16x8 pa2, bf16x8 pa3) {
;     __builtin_amdgcn_s_setprio(1);
;     pv_ks<0>(o, vb, pa0); pv_ks<1>(o, vb, pa1); pv_ks<2>(o, vb, pa2); pv_ks<3>(o, vb, pa3);
;     __builtin_amdgcn_s_setprio(0);
; }
; __device__ __forceinline__ void exp_half(f32x16& p) {
; #pragma unroll
;     for (int r = 0; r < 16; ++r) p[r] = __builtin_amdgcn_exp2f(p[r]);
; }
; __device__ __forceinline__ void pack_p(const f32x16& p0, const f32x16& p1, float& l_reg, bf16x8& pa0, bf16x8& pa1, bf16x8& pa2, bf16x8& pa3) {
;     float ps = 0;
; #pragma unroll
;     for (int r = 0; r < 16; ++r) ps += p0[r];
; #pragma unroll
;     for (int r = 0; r < 16; ++r) ps += p1[r];
;     l_reg += ps;
;     ...
;     PK4(p0, 0, pa0); PK4(p0, 8, pa1); PK4(p1, 0, pa2); PK4(p1, 8, pa3);
;     ...
; }
; template <int ND0> __device__ __forceinline__ void qkt(f32x16& p0, f32x16& p1, const char* Ks, const bf16x8* qr, int r32, int hi, int colB0) {
; #pragma unroll
;     for (int d0 = 0; d0 < ND0; ++d0) { const int cb = colB0 + (d0 * 16 + hi * 8) * 2;
;         const bf16x8 b0 = *reinterpret_cast<const bf16x8*>(Ks + KSWZ(r32, cb));
;         const bf16x8 b1 = *reinterpret_cast<const bf16x8*>(Ks + KSWZ(32 + r32, cb));
;         p0 = __builtin_amdgcn_mfma_f32_32x32x16_bf16(b0, qr[d0], p0, 0, 0, 0);
.Lsym_biasdone_ys3:
	s_add_i32 s55, s55, 64
	v_add_f32_e32 v183, 0xc2800000, v183
	ds_read_b64_tr_b16 v[144:145], v252 offset:49152
	ds_read_b64_tr_b16 v[146:147], v252 offset:51200
	ds_read_b64_tr_b16 v[148:149], v252 offset:49664
	ds_read_b64_tr_b16 v[150:151], v252 offset:51712
	ds_read_b64_tr_b16 v[152:153], v252 offset:50176
	ds_read_b64_tr_b16 v[154:155], v252 offset:52224
	ds_read_b64_tr_b16 v[156:157], v252 offset:50688
	ds_read_b64_tr_b16 v[158:159], v252 offset:52736
	s_setprio 0
	s_waitcnt lgkmcnt(4)
	v_mfma_f32_32x32x16_bf16 v[48:63], v[128:131], v[144:147], v[48:63]
	ds_read_b64_tr_b16 v[144:145], v252 offset:53248
	ds_read_b64_tr_b16 v[146:147], v252 offset:55296
	v_exp_f32_e32 v120, v120
	v_exp_f32_e32 v121, v121
	v_mfma_f32_32x32x16_bf16 v[32:47], v[128:131], v[148:151], v[32:47]
	ds_read_b64_tr_b16 v[148:149], v252 offset:53760
	ds_read_b64_tr_b16 v[150:151], v252 offset:55808
	v_exp_f32_e32 v122, v122
	v_exp_f32_e32 v123, v123
	v_add_f32_e32 v182, v120, v182
	v_add_f32_e32 v182, v121, v182
	v_cvt_pk_bf16_f32 v132, v120, v121
	s_waitcnt lgkmcnt(4)
	v_mfma_f32_32x32x16_bf16 v[16:31], v[128:131], v[152:155], v[16:31]
	ds_read_b64_tr_b16 v[152:153], v252 offset:54272
	ds_read_b64_tr_b16 v[154:155], v252 offset:56320
	v_exp_f32_e32 v124, v124
	v_exp_f32_e32 v125, v125
	v_add_f32_e32 v182, v122, v182
	v_add_f32_e32 v182, v123, v182
	v_cvt_pk_bf16_f32 v133, v122, v123
	v_mfma_f32_32x32x16_bf16 v[0:15], v[128:131], v[156:159], v[0:15]
	ds_read_b64_tr_b16 v[156:157], v252 offset:54784
	ds_read_b64_tr_b16 v[158:159], v252 offset:56832
	v_exp_f32_e32 v126, v126
	v_exp_f32_e32 v127, v127
	v_add_f32_e32 v182, v124, v182
	v_add_f32_e32 v182, v125, v182
	v_cvt_pk_bf16_f32 v134, v124, v125
	v_cvt_pk_bf16_f32 v135, v126, v127
	v_add_f32_e32 v182, v126, v182
	v_add_f32_e32 v182, v127, v182
	v_mfma_f32_32x32x16_bf16 v[80:95], v[192:195], v[172:175], v[80:95]
	v_mfma_f32_32x32x16_bf16 v[64:79], v[196:199], v[172:175], v[64:79]
	v_mfma_f32_32x32x16_bf16 v[80:95], v[200:203], v[168:171], v[80:95]
	v_mfma_f32_32x32x16_bf16 v[64:79], v[204:207], v[168:171], v[64:79]
	s_setprio 1
	s_waitcnt lgkmcnt(4)
	v_mfma_f32_32x32x16_bf16 v[48:63], v[132:135], v[144:147], v[48:63]
	ds_read_b64_tr_b16 v[144:145], v252 offset:57344
	ds_read_b64_tr_b16 v[146:147], v252 offset:59392
	v_exp_f32_e32 v96, v96
	v_exp_f32_e32 v97, v97
	v_mfma_f32_32x32x16_bf16 v[32:47], v[132:135], v[148:151], v[32:47]
	ds_read_b64_tr_b16 v[148:149], v252 offset:57856
	ds_read_b64_tr_b16 v[150:151], v252 offset:59904
	v_exp_f32_e32 v98, v98
	v_exp_f32_e32 v99, v99
	v_add_f32_e32 v182, v96, v182
	v_add_f32_e32 v182, v97, v182
	v_cvt_pk_bf16_f32 v136, v96, v97
	s_waitcnt lgkmcnt(4)
	v_mfma_f32_32x32x16_bf16 v[16:31], v[132:135], v[152:155], v[16:31]
	ds_read_b64_tr_b16 v[152:153], v252 offset:58368
	ds_read_b64_tr_b16 v[154:155], v252 offset:60416
	v_exp_f32_e32 v100, v100
	v_exp_f32_e32 v101, v101
	v_add_f32_e32 v182, v98, v182
	v_add_f32_e32 v182, v99, v182
	v_cvt_pk_bf16_f32 v137, v98, v99
	v_mfma_f32_32x32x16_bf16 v[0:15], v[132:135], v[156:159], v[0:15]
	ds_read_b64_tr_b16 v[156:157], v252 offset:58880
	ds_read_b64_tr_b16 v[158:159], v252 offset:60928
	v_exp_f32_e32 v102, v102
	v_exp_f32_e32 v103, v103
	v_add_f32_e32 v182, v100, v182
	v_add_f32_e32 v182, v101, v182
	v_cvt_pk_bf16_f32 v138, v100, v101
	v_cvt_pk_bf16_f32 v139, v102, v103
	v_add_f32_e32 v182, v102, v182
	v_add_f32_e32 v182, v103, v182
	v_mfma_f32_32x32x16_bf16 v[80:95], v[208:211], v[164:167], v[80:95]
	v_mfma_f32_32x32x16_bf16 v[64:79], v[212:215], v[164:167], v[64:79]
	v_mfma_f32_32x32x16_bf16 v[80:95], v[216:219], v[160:163], v[80:95]
	v_mfma_f32_32x32x16_bf16 v[64:79], v[220:223], v[160:163], v[64:79]
	s_setprio 0
	s_waitcnt lgkmcnt(4)
	v_mfma_f32_32x32x16_bf16 v[48:63], v[136:139], v[144:147], v[48:63]
	ds_read_b64_tr_b16 v[144:145], v252 offset:61440
	ds_read_b64_tr_b16 v[146:147], v252 offset:63488
	v_exp_f32_e32 v104, v104
	v_exp_f32_e32 v105, v105
	v_mfma_f32_32x32x16_bf16 v[32:47], v[136:139], v[148:151], v[32:47]
	ds_read_b64_tr_b16 v[148:149], v252 offset:61952
	ds_read_b64_tr_b16 v[150:151], v252 offset:64000
	v_exp_f32_e32 v106, v106
	v_exp_f32_e32 v107, v107
	v_add_f32_e32 v182, v104, v182
	v_add_f32_e32 v182, v105, v182
	v_cvt_pk_bf16_f32 v140, v104, v105
	s_waitcnt lgkmcnt(4)
	v_mfma_f32_32x32x16_bf16 v[16:31], v[136:139], v[152:155], v[16:31]
	ds_read_b64_tr_b16 v[152:153], v252 offset:62464
	ds_read_b64_tr_b16 v[154:155], v252 offset:64512
	v_exp_f32_e32 v108, v108
	v_exp_f32_e32 v109, v109
	v_add_f32_e32 v182, v106, v182
	v_add_f32_e32 v182, v107, v182
	v_cvt_pk_bf16_f32 v141, v106, v107
	v_mfma_f32_32x32x16_bf16 v[0:15], v[136:139], v[156:159], v[0:15]
	ds_read_b64_tr_b16 v[156:157], v252 offset:62976
	ds_read_b64_tr_b16 v[158:159], v252 offset:65024
	v_exp_f32_e32 v110, v110
	v_exp_f32_e32 v111, v111
	v_add_f32_e32 v182, v108, v182
	v_add_f32_e32 v182, v109, v182
	v_cvt_pk_bf16_f32 v142, v108, v109
	v_cvt_pk_bf16_f32 v143, v110, v111
	v_add_f32_e32 v182, v110, v182
	v_add_f32_e32 v182, v111, v182
	s_setprio 1
	s_waitcnt lgkmcnt(4)
	v_mfma_f32_32x32x16_bf16 v[48:63], v[140:143], v[144:147], v[48:63]
	v_exp_f32_e32 v80, v80
	v_exp_f32_e32 v81, v81
	v_mfma_f32_32x32x16_bf16 v[32:47], v[140:143], v[148:151], v[32:47]
	v_exp_f32_e32 v82, v82
	v_exp_f32_e32 v83, v83
	v_add_f32_e32 v182, v80, v182
	v_add_f32_e32 v182, v81, v182
	v_cvt_pk_bf16_f32 v128, v80, v81
	s_waitcnt lgkmcnt(0)
	v_mfma_f32_32x32x16_bf16 v[16:31], v[140:143], v[152:155], v[16:31]
	v_exp_f32_e32 v84, v84
	v_exp_f32_e32 v85, v85
	v_add_f32_e32 v182, v82, v182
	v_add_f32_e32 v182, v83, v182
	v_cvt_pk_bf16_f32 v129, v82, v83
	v_mfma_f32_32x32x16_bf16 v[0:15], v[140:143], v[156:159], v[0:15]
	v_exp_f32_e32 v86, v86
	v_exp_f32_e32 v87, v87
	v_add_f32_e32 v182, v84, v182
	v_add_f32_e32 v182, v85, v182
	v_cvt_pk_bf16_f32 v130, v84, v85
	v_cvt_pk_bf16_f32 v131, v86, v87
	v_add_f32_e32 v182, v86, v182
	v_add_f32_e32 v182, v87, v182
	s_add_i32 s54, s54, 1
	s_branch .Lsym_loop_y
; #define SBAR() __builtin_amdgcn_sched_barrier(0)
; #define PK4(P, BASE, OUT) do { u32x4 w = {cvtpk(P[BASE + 0], P[BASE + 1]), cvtpk(P[BASE + 2], P[BASE + 3]), cvtpk(P[BASE + 4], P[BASE + 5]), cvtpk(P[BASE + 6], P[BASE + 7])}; \
;     OUT = *reinterpret_cast<bf16x8*>(&w); } while (0)
; template <int KS> __device__ __forceinline__ void pv_ks(f32x16* o, int vb, bf16x8 pa) {
;     const s16x4 l0 = tr_read<v_rd_off(0, KS, 0)>(vb), h0 = tr_read<v_rd_off(0, KS, 1)>(vb), l1 = tr_read<v_rd_off(1, KS, 0)>(vb), h1 = tr_read<v_rd_off(1, KS, 1)>(vb);
;     const s16x4 l2 = tr_read<v_rd_off(2, KS, 0)>(vb), h2 = tr_read<v_rd_off(2, KS, 1)>(vb), l3 = tr_read<v_rd_off(3, KS, 0)>(vb), h3 = tr_read<v_rd_off(3, KS, 1)>(vb);
;     ...
;     asm volatile("s_waitcnt lgkmcnt(6)" ::: "memory"); SBAR();
;     o[0] = __builtin_amdgcn_mfma_f32_32x32x16_bf16(pa, PK(l0, h0), o[0], 0, 0, 0);
;     asm volatile("s_waitcnt lgkmcnt(4)" ::: "memory"); SBAR();
;     o[1] = __builtin_amdgcn_mfma_f32_32x32x16_bf16(pa, PK(l1, h1), o[1], 0, 0, 0);
;     asm volatile("s_waitcnt lgkmcnt(2)" ::: "memory"); SBAR();
;     o[2] = __builtin_amdgcn_mfma_f32_32x32x16_bf16(pa, PK(l2, h2), o[2], 0, 0, 0);
;     asm volatile("s_waitcnt lgkmcnt(0)" ::: "memory"); SBAR();
;     o[3] = __builtin_amdgcn_mfma_f32_32x32x16_bf16(pa, PK(l3, h3), o[3], 0, 0, 0);
;     ...
; }
; __device__ __forceinline__ void pv_d0(f32x16* o, int vb, bf16x8 pa0, bf16x8 pa1, bf16x8 pa2, bf16x8 pa3) {
;     __builtin_amdgcn_s_setprio(1);
;     pv_ks<0>(o, vb, pa0); pv_ks<1>(o, vb, pa1); pv_ks<2>(o, vb, pa2); pv_ks<3>(o, vb, pa3);
;     __builtin_amdgcn_s_setprio(0);
; }
; __device__ __forceinline__ void exp_half(f32x16& p) {
; #pragma unroll
;     for (int r = 0; r < 16; ++r) p[r] = __builtin_amdgcn_exp2f(p[r]);
; }
; __device__ __forceinline__ void pack_p(const f32x16& p0, const f32x16& p1, float& l_reg, bf16x8& pa0, bf16x8& pa1, bf16x8& pa2, bf16x8& pa3) {
;     float ps = 0;
; #pragma unroll
;     for (int r = 0; r < 16; ++r) ps += p0[r];
; #pragma unroll
;     for (int r = 0; r < 16; ++r) ps += p1[r];
;     l_reg += ps;
;     ...
;     PK4(p0, 0, pa0); PK4(p0, 8, pa1); PK4(p1, 0, pa2); PK4(p1, 8, pa3);
;     ...
; }
.Lsym_last1_y:
	s_waitcnt vmcnt(0)
	s_barrier
	ds_read_b64_tr_b16 v[144:145], v252 offset:16384
	ds_read_b64_tr_b16 v[146:147], v252 offset:18432
	ds_read_b64_tr_b16 v[148:149], v252 offset:16896
	ds_read_b64_tr_b16 v[150:151], v252 offset:18944
	ds_read_b64_tr_b16 v[152:153], v252 offset:17408
	ds_read_b64_tr_b16 v[154:155], v252 offset:19456
	ds_read_b64_tr_b16 v[156:157], v252 offset:17920
	ds_read_b64_tr_b16 v[158:159], v252 offset:19968
	s_setprio 0
	s_waitcnt lgkmcnt(4)
	v_mfma_f32_32x32x16_bf16 v[48:63], v[128:131], v[144:147], v[48:63]
	ds_read_b64_tr_b16 v[144:145], v252 offset:20480
	ds_read_b64_tr_b16 v[146:147], v252 offset:22528
	v_exp_f32_e32 v120, v120
	v_exp_f32_e32 v121, v121
	v_mfma_f32_32x32x16_bf16 v[32:47], v[128:131], v[148:151], v[32:47]
	ds_read_b64_tr_b16 v[148:149], v252 offset:20992
	ds_read_b64_tr_b16 v[150:151], v252 offset:23040
	v_exp_f32_e32 v122, v122
	v_exp_f32_e32 v123, v123
	v_add_f32_e32 v182, v120, v182
	v_add_f32_e32 v182, v121, v182
	v_cvt_pk_bf16_f32 v132, v120, v121
	s_waitcnt lgkmcnt(4)
	v_mfma_f32_32x32x16_bf16 v[16:31], v[128:131], v[152:155], v[16:31]
	ds_read_b64_tr_b16 v[152:153], v252 offset:21504
	ds_read_b64_tr_b16 v[154:155], v252 offset:23552
	v_exp_f32_e32 v124, v124
	v_exp_f32_e32 v125, v125
	v_add_f32_e32 v182, v122, v182
	v_add_f32_e32 v182, v123, v182
	v_cvt_pk_bf16_f32 v133, v122, v123
	v_mfma_f32_32x32x16_bf16 v[0:15], v[128:131], v[156:159], v[0:15]
	ds_read_b64_tr_b16 v[156:157], v252 offset:22016
	ds_read_b64_tr_b16 v[158:159], v252 offset:24064
	v_exp_f32_e32 v126, v126
	v_exp_f32_e32 v127, v127
	v_add_f32_e32 v182, v124, v182
	v_add_f32_e32 v182, v125, v182
	v_cvt_pk_bf16_f32 v134, v124, v125
	v_cvt_pk_bf16_f32 v135, v126, v127
	v_add_f32_e32 v182, v126, v182
	v_add_f32_e32 v182, v127, v182
	s_setprio 1
	s_waitcnt lgkmcnt(4)
	v_mfma_f32_32x32x16_bf16 v[48:63], v[132:135], v[144:147], v[48:63]
	ds_read_b64_tr_b16 v[144:145], v252 offset:24576
	ds_read_b64_tr_b16 v[146:147], v252 offset:26624
	v_exp_f32_e32 v96, v96
	v_exp_f32_e32 v97, v97
	v_mfma_f32_32x32x16_bf16 v[32:47], v[132:135], v[148:151], v[32:47]
	ds_read_b64_tr_b16 v[148:149], v252 offset:25088
	ds_read_b64_tr_b16 v[150:151], v252 offset:27136
	v_exp_f32_e32 v98, v98
	v_exp_f32_e32 v99, v99
	v_add_f32_e32 v182, v96, v182
	v_add_f32_e32 v182, v97, v182
	v_cvt_pk_bf16_f32 v136, v96, v97
	s_waitcnt lgkmcnt(4)
	v_mfma_f32_32x32x16_bf16 v[16:31], v[132:135], v[152:155], v[16:31]
	ds_read_b64_tr_b16 v[152:153], v252 offset:25600
	ds_read_b64_tr_b16 v[154:155], v252 offset:27648
	v_exp_f32_e32 v100, v100
	v_exp_f32_e32 v101, v101
	v_add_f32_e32 v182, v98, v182
	v_add_f32_e32 v182, v99, v182
	v_cvt_pk_bf16_f32 v137, v98, v99
	v_mfma_f32_32x32x16_bf16 v[0:15], v[132:135], v[156:159], v[0:15]
	ds_read_b64_tr_b16 v[156:157], v252 offset:26112
	ds_read_b64_tr_b16 v[158:159], v252 offset:28160
	v_exp_f32_e32 v102, v102
	v_exp_f32_e32 v103, v103
	v_add_f32_e32 v182, v100, v182
	v_add_f32_e32 v182, v101, v182
	v_cvt_pk_bf16_f32 v138, v100, v101
	v_cvt_pk_bf16_f32 v139, v102, v103
	v_add_f32_e32 v182, v102, v182
	v_add_f32_e32 v182, v103, v182
	s_setprio 0
	s_waitcnt lgkmcnt(4)
	v_mfma_f32_32x32x16_bf16 v[48:63], v[136:139], v[144:147], v[48:63]
	ds_read_b64_tr_b16 v[144:145], v252 offset:28672
	ds_read_b64_tr_b16 v[146:147], v252 offset:30720
	v_exp_f32_e32 v104, v104
	v_exp_f32_e32 v105, v105
	v_mfma_f32_32x32x16_bf16 v[32:47], v[136:139], v[148:151], v[32:47]
	ds_read_b64_tr_b16 v[148:149], v252 offset:29184
	ds_read_b64_tr_b16 v[150:151], v252 offset:31232
	v_exp_f32_e32 v106, v106
	v_exp_f32_e32 v107, v107
	v_add_f32_e32 v182, v104, v182
	v_add_f32_e32 v182, v105, v182
	v_cvt_pk_bf16_f32 v140, v104, v105
	s_waitcnt lgkmcnt(4)
	v_mfma_f32_32x32x16_bf16 v[16:31], v[136:139], v[152:155], v[16:31]
	ds_read_b64_tr_b16 v[152:153], v252 offset:29696
	ds_read_b64_tr_b16 v[154:155], v252 offset:31744
	v_exp_f32_e32 v108, v108
	v_exp_f32_e32 v109, v109
	v_add_f32_e32 v182, v106, v182
	v_add_f32_e32 v182, v107, v182
	v_cvt_pk_bf16_f32 v141, v106, v107
	v_mfma_f32_32x32x16_bf16 v[0:15], v[136:139], v[156:159], v[0:15]
	ds_read_b64_tr_b16 v[156:157], v252 offset:30208
	ds_read_b64_tr_b16 v[158:159], v252 offset:32256
	v_exp_f32_e32 v110, v110
	v_exp_f32_e32 v111, v111
	v_add_f32_e32 v182, v108, v182
	v_add_f32_e32 v182, v109, v182
	v_cvt_pk_bf16_f32 v142, v108, v109
	v_cvt_pk_bf16_f32 v143, v110, v111
	v_add_f32_e32 v182, v110, v182
	v_add_f32_e32 v182, v111, v182
	s_setprio 1
	s_waitcnt lgkmcnt(4)
	v_mfma_f32_32x32x16_bf16 v[48:63], v[140:143], v[144:147], v[48:63]
	v_mfma_f32_32x32x16_bf16 v[32:47], v[140:143], v[148:151], v[32:47]
	s_waitcnt lgkmcnt(0)
	v_mfma_f32_32x32x16_bf16 v[16:31], v[140:143], v[152:155], v[16:31]
	v_mfma_f32_32x32x16_bf16 v[0:15], v[140:143], v[156:159], v[0:15]
	s_branch .Lsym_done
; #define SBAR() __builtin_amdgcn_sched_barrier(0)
; #define PK4(P, BASE, OUT) do { u32x4 w = {cvtpk(P[BASE + 0], P[BASE + 1]), cvtpk(P[BASE + 2], P[BASE + 3]), cvtpk(P[BASE + 4], P[BASE + 5]), cvtpk(P[BASE + 6], P[BASE + 7])}; \
;     OUT = *reinterpret_cast<bf16x8*>(&w); } while (0)
; template <int KS> __device__ __forceinline__ void pv_ks(f32x16* o, int vb, bf16x8 pa) {
;     const s16x4 l0 = tr_read<v_rd_off(0, KS, 0)>(vb), h0 = tr_read<v_rd_off(0, KS, 1)>(vb), l1 = tr_read<v_rd_off(1, KS, 0)>(vb), h1 = tr_read<v_rd_off(1, KS, 1)>(vb);
;     const s16x4 l2 = tr_read<v_rd_off(2, KS, 0)>(vb), h2 = tr_read<v_rd_off(2, KS, 1)>(vb), l3 = tr_read<v_rd_off(3, KS, 0)>(vb), h3 = tr_read<v_rd_off(3, KS, 1)>(vb);
;     ...
;     asm volatile("s_waitcnt lgkmcnt(6)" ::: "memory"); SBAR();
;     o[0] = __builtin_amdgcn_mfma_f32_32x32x16_bf16(pa, PK(l0, h0), o[0], 0, 0, 0);
;     asm volatile("s_waitcnt lgkmcnt(4)" ::: "memory"); SBAR();
;     o[1] = __builtin_amdgcn_mfma_f32_32x32x16_bf16(pa, PK(l1, h1), o[1], 0, 0, 0);
;     asm volatile("s_waitcnt lgkmcnt(2)" ::: "memory"); SBAR();
;     o[2] = __builtin_amdgcn_mfma_f32_32x32x16_bf16(pa, PK(l2, h2), o[2], 0, 0, 0);
;     asm volatile("s_waitcnt lgkmcnt(0)" ::: "memory"); SBAR();
;     o[3] = __builtin_amdgcn_mfma_f32_32x32x16_bf16(pa, PK(l3, h3), o[3], 0, 0, 0);
;     ...
; }
; __device__ __forceinline__ void pv_d0(f32x16* o, int vb, bf16x8 pa0, bf16x8 pa1, bf16x8 pa2, bf16x8 pa3) {
;     __builtin_amdgcn_s_setprio(1);
;     pv_ks<0>(o, vb, pa0); pv_ks<1>(o, vb, pa1); pv_ks<2>(o, vb, pa2); pv_ks<3>(o, vb, pa3);
;     __builtin_amdgcn_s_setprio(0);
; }
; __device__ __forceinline__ void exp_half(f32x16& p) {
; #pragma unroll
;     for (int r = 0; r < 16; ++r) p[r] = __builtin_amdgcn_exp2f(p[r]);
; }
; __device__ __forceinline__ void pack_p(const f32x16& p0, const f32x16& p1, float& l_reg, bf16x8& pa0, bf16x8& pa1, bf16x8& pa2, bf16x8& pa3) {
;     float ps = 0;
; #pragma unroll
;     for (int r = 0; r < 16; ++r) ps += p0[r];
; #pragma unroll
;     for (int r = 0; r < 16; ++r) ps += p1[r];
;     l_reg += ps;
;     ...
;     PK4(p0, 0, pa0); PK4(p0, 8, pa1); PK4(p1, 0, pa2); PK4(p1, 8, pa3);
;     ...
; }
.Lsym_last3_y:
	s_waitcnt vmcnt(0)
	s_barrier
	ds_read_b64_tr_b16 v[144:145], v252 offset:49152
	ds_read_b64_tr_b16 v[146:147], v252 offset:51200
	ds_read_b64_tr_b16 v[148:149], v252 offset:49664
	ds_read_b64_tr_b16 v[150:151], v252 offset:51712
	ds_read_b64_tr_b16 v[152:153], v252 offset:50176
	ds_read_b64_tr_b16 v[154:155], v252 offset:52224
	ds_read_b64_tr_b16 v[156:157], v252 offset:50688
	ds_read_b64_tr_b16 v[158:159], v252 offset:52736
	s_setprio 0
	s_waitcnt lgkmcnt(4)
	v_mfma_f32_32x32x16_bf16 v[48:63], v[128:131], v[144:147], v[48:63]
	ds_read_b64_tr_b16 v[144:145], v252 offset:53248
	ds_read_b64_tr_b16 v[146:147], v252 offset:55296
	v_exp_f32_e32 v120, v120
	v_exp_f32_e32 v121, v121
	v_mfma_f32_32x32x16_bf16 v[32:47], v[128:131], v[148:151], v[32:47]
	ds_read_b64_tr_b16 v[148:149], v252 offset:53760
	ds_read_b64_tr_b16 v[150:151], v252 offset:55808
	v_exp_f32_e32 v122, v122
	v_exp_f32_e32 v123, v123
	v_add_f32_e32 v182, v120, v182
	v_add_f32_e32 v182, v121, v182
	v_cvt_pk_bf16_f32 v132, v120, v121
	s_waitcnt lgkmcnt(4)
	v_mfma_f32_32x32x16_bf16 v[16:31], v[128:131], v[152:155], v[16:31]
	ds_read_b64_tr_b16 v[152:153], v252 offset:54272
	ds_read_b64_tr_b16 v[154:155], v252 offset:56320
	v_exp_f32_e32 v124, v124
	v_exp_f32_e32 v125, v125
	v_add_f32_e32 v182, v122, v182
	v_add_f32_e32 v182, v123, v182
	v_cvt_pk_bf16_f32 v133, v122, v123
	v_mfma_f32_32x32x16_bf16 v[0:15], v[128:131], v[156:159], v[0:15]
	ds_read_b64_tr_b16 v[156:157], v252 offset:54784
	ds_read_b64_tr_b16 v[158:159], v252 offset:56832
	v_exp_f32_e32 v126, v126
	v_exp_f32_e32 v127, v127
	v_add_f32_e32 v182, v124, v182
	v_add_f32_e32 v182, v125, v182
	v_cvt_pk_bf16_f32 v134, v124, v125
	v_cvt_pk_bf16_f32 v135, v126, v127
	v_add_f32_e32 v182, v126, v182
	v_add_f32_e32 v182, v127, v182
	s_setprio 1
	s_waitcnt lgkmcnt(4)
	v_mfma_f32_32x32x16_bf16 v[48:63], v[132:135], v[144:147], v[48:63]
	ds_read_b64_tr_b16 v[144:145], v252 offset:57344
	ds_read_b64_tr_b16 v[146:147], v252 offset:59392
	v_exp_f32_e32 v96, v96
	v_exp_f32_e32 v97, v97
	v_mfma_f32_32x32x16_bf16 v[32:47], v[132:135], v[148:151], v[32:47]
	ds_read_b64_tr_b16 v[148:149], v252 offset:57856
	ds_read_b64_tr_b16 v[150:151], v252 offset:59904
	v_exp_f32_e32 v98, v98
	v_exp_f32_e32 v99, v99
	v_add_f32_e32 v182, v96, v182
	v_add_f32_e32 v182, v97, v182
	v_cvt_pk_bf16_f32 v136, v96, v97
	s_waitcnt lgkmcnt(4)
	v_mfma_f32_32x32x16_bf16 v[16:31], v[132:135], v[152:155], v[16:31]
	ds_read_b64_tr_b16 v[152:153], v252 offset:58368
	ds_read_b64_tr_b16 v[154:155], v252 offset:60416
	v_exp_f32_e32 v100, v100
	v_exp_f32_e32 v101, v101
	v_add_f32_e32 v182, v98, v182
	v_add_f32_e32 v182, v99, v182
	v_cvt_pk_bf16_f32 v137, v98, v99
	v_mfma_f32_32x32x16_bf16 v[0:15], v[132:135], v[156:159], v[0:15]
	ds_read_b64_tr_b16 v[156:157], v252 offset:58880
	ds_read_b64_tr_b16 v[158:159], v252 offset:60928
	v_exp_f32_e32 v102, v102
	v_exp_f32_e32 v103, v103
	v_add_f32_e32 v182, v100, v182
	v_add_f32_e32 v182, v101, v182
	v_cvt_pk_bf16_f32 v138, v100, v101
	v_cvt_pk_bf16_f32 v139, v102, v103
	v_add_f32_e32 v182, v102, v182
	v_add_f32_e32 v182, v103, v182
	s_setprio 0
	s_waitcnt lgkmcnt(4)
	v_mfma_f32_32x32x16_bf16 v[48:63], v[136:139], v[144:147], v[48:63]
	ds_read_b64_tr_b16 v[144:145], v252 offset:61440
	ds_read_b64_tr_b16 v[146:147], v252 offset:63488
	v_exp_f32_e32 v104, v104
	v_exp_f32_e32 v105, v105
	v_mfma_f32_32x32x16_bf16 v[32:47], v[136:139], v[148:151], v[32:47]
	ds_read_b64_tr_b16 v[148:149], v252 offset:61952
	ds_read_b64_tr_b16 v[150:151], v252 offset:64000
	v_exp_f32_e32 v106, v106
	v_exp_f32_e32 v107, v107
	v_add_f32_e32 v182, v104, v182
	v_add_f32_e32 v182, v105, v182
	v_cvt_pk_bf16_f32 v140, v104, v105
	s_waitcnt lgkmcnt(4)
	v_mfma_f32_32x32x16_bf16 v[16:31], v[136:139], v[152:155], v[16:31]
	ds_read_b64_tr_b16 v[152:153], v252 offset:62464
	ds_read_b64_tr_b16 v[154:155], v252 offset:64512
	v_exp_f32_e32 v108, v108
	v_exp_f32_e32 v109, v109
	v_add_f32_e32 v182, v106, v182
	v_add_f32_e32 v182, v107, v182
	v_cvt_pk_bf16_f32 v141, v106, v107
	v_mfma_f32_32x32x16_bf16 v[0:15], v[136:139], v[156:159], v[0:15]
	ds_read_b64_tr_b16 v[156:157], v252 offset:62976
	ds_read_b64_tr_b16 v[158:159], v252 offset:65024
	v_exp_f32_e32 v110, v110
	v_exp_f32_e32 v111, v111
	v_add_f32_e32 v182, v108, v182
	v_add_f32_e32 v182, v109, v182
	v_cvt_pk_bf16_f32 v142, v108, v109
	v_cvt_pk_bf16_f32 v143, v110, v111
	v_add_f32_e32 v182, v110, v182
	v_add_f32_e32 v182, v111, v182
	s_setprio 1
	s_waitcnt lgkmcnt(4)
	v_mfma_f32_32x32x16_bf16 v[48:63], v[140:143], v[144:147], v[48:63]
	v_mfma_f32_32x32x16_bf16 v[32:47], v[140:143], v[148:151], v[32:47]
	s_waitcnt lgkmcnt(0)
	v_mfma_f32_32x32x16_bf16 v[16:31], v[140:143], v[152:155], v[16:31]
	v_mfma_f32_32x32x16_bf16 v[0:15], v[140:143], v[156:159], v[0:15]
	s_branch .Lsym_done
